# main GEMM K-loops: drop per-phase s_setprio flips and the duplicate lgkmcnt(0) after them (issue slots only)
# speedup vs baseline: 1.0052x; 1.0052x over previous
.Lpeel_p1:
	ds_read_b128 v[130:133], v173
	ds_read_b128 v[134:137], v173 offset:1024
	ds_read_b128 v[138:141], v173 offset:2048
	ds_read_b128 v[142:145], v173 offset:3072
	s_add_u32 s6, s2, 0xfffc0080
	s_addc_u32 s7, s3, -1
	s_cmp_eq_u32 s73, 12
	s_cselect_b32 s9, s1, s7
	s_cselect_b32 s8, s33, s6
	s_cselect_b32 s7, s39, s72
	s_cselect_b32 s6, s41, s71
	s_add_i32 m0, s50, 0xc000
	ds_read_b128 v[180:183], v175
	ds_read_b128 v[184:187], v175 offset:1024
	ds_read_b128 v[190:193], v175 offset:2048
	ds_read_b128 v[194:197], v175 offset:3072
	ds_read_b128 v[198:201], v175 offset:4096
	ds_read_b128 v[202:205], v175 offset:5120
	ds_read_b128 v[206:209], v175 offset:6144
	ds_read_b128 v[210:213], v175 offset:7168
	global_load_lds_dwordx4 v156, s[2:3]
	s_add_i32 m0, s50, 0xe000
	s_nop 0
	global_load_lds_dwordx4 v158, s[2:3]
	s_waitcnt lgkmcnt(8)
	s_barrier
	s_waitcnt lgkmcnt(0)
	v_mfma_f32_16x16x32_bf16 v[126:129], v[130:133], v[180:183], 0
	v_mfma_f32_16x16x32_bf16 v[122:125], v[138:141], v[180:183], 0
	v_mfma_f32_16x16x32_bf16 v[118:121], v[130:133], v[190:193], 0
	v_mfma_f32_16x16x32_bf16 v[110:113], v[138:141], v[190:193], 0
	v_mfma_f32_16x16x32_bf16 v[102:105], v[130:133], v[198:201], 0
	v_mfma_f32_16x16x32_bf16 v[94:97], v[138:141], v[198:201], 0
	v_mfma_f32_16x16x32_bf16 v[86:89], v[130:133], v[206:209], 0
	v_mfma_f32_16x16x32_bf16 v[78:81], v[138:141], v[206:209], 0
	v_mfma_f32_16x16x32_bf16 v[126:129], v[134:137], v[184:187], v[126:129]
	v_mfma_f32_16x16x32_bf16 v[122:125], v[142:145], v[184:187], v[122:125]
	v_mfma_f32_16x16x32_bf16 v[118:121], v[134:137], v[194:197], v[118:121]
	v_mfma_f32_16x16x32_bf16 v[110:113], v[142:145], v[194:197], v[110:113]
	v_mfma_f32_16x16x32_bf16 v[102:105], v[134:137], v[202:205], v[102:105]
	v_mfma_f32_16x16x32_bf16 v[94:97], v[142:145], v[202:205], v[94:97]
	v_mfma_f32_16x16x32_bf16 v[86:89], v[134:137], v[210:213], v[86:89]
	v_mfma_f32_16x16x32_bf16 v[78:81], v[142:145], v[210:213], v[78:81]
	s_barrier
	s_add_i32 s74, s66, s49
	s_add_u32 s98, s6, 0x80
	s_addc_u32 s99, s7, 0
	s_mov_b32 m0, s74
	ds_read_b128 v[214:217], v177
	ds_read_b128 v[218:221], v177 offset:1024
	ds_read_b128 v[222:225], v177 offset:2048
	ds_read_b128 v[226:229], v177 offset:3072
	global_load_lds_dwordx4 v148, s[6:7]
	s_add_i32 m0, s74, 0x2000
	s_nop 0
	global_load_lds_dwordx4 v152, s[6:7]
	s_barrier
	s_waitcnt lgkmcnt(0)
	v_mfma_f32_16x16x32_bf16 v[114:117], v[214:217], v[180:183], 0
	v_mfma_f32_16x16x32_bf16 v[106:109], v[222:225], v[180:183], 0
	v_mfma_f32_16x16x32_bf16 v[98:101], v[214:217], v[190:193], 0
	v_mfma_f32_16x16x32_bf16 v[90:93], v[222:225], v[190:193], 0
	v_mfma_f32_16x16x32_bf16 v[82:85], v[214:217], v[198:201], 0
	v_mfma_f32_16x16x32_bf16 v[74:77], v[222:225], v[198:201], 0
	v_mfma_f32_16x16x32_bf16 v[70:73], v[214:217], v[206:209], 0
	v_mfma_f32_16x16x32_bf16 v[66:69], v[222:225], v[206:209], 0
	v_mfma_f32_16x16x32_bf16 v[114:117], v[218:221], v[184:187], v[114:117]
	v_mfma_f32_16x16x32_bf16 v[106:109], v[226:229], v[184:187], v[106:109]
	v_mfma_f32_16x16x32_bf16 v[98:101], v[218:221], v[194:197], v[98:101]
	v_mfma_f32_16x16x32_bf16 v[90:93], v[226:229], v[194:197], v[90:93]
	v_mfma_f32_16x16x32_bf16 v[82:85], v[218:221], v[202:205], v[82:85]
	v_mfma_f32_16x16x32_bf16 v[74:77], v[226:229], v[202:205], v[74:77]
	v_mfma_f32_16x16x32_bf16 v[70:73], v[218:221], v[210:213], v[70:73]
	v_mfma_f32_16x16x32_bf16 v[66:69], v[226:229], v[210:213], v[66:69]
	s_mov_b32 m0, s50
	s_add_u32 s100, s8, 0x80
	s_addc_u32 s101, s9, 0
	s_barrier
	ds_read_b128 v[180:183], v175 offset:16384
	ds_read_b128 v[184:187], v175 offset:17408
	ds_read_b128 v[190:193], v175 offset:18432
	ds_read_b128 v[194:197], v175 offset:19456
	ds_read_b128 v[198:201], v175 offset:20480
	ds_read_b128 v[202:205], v175 offset:21504
	ds_read_b128 v[206:209], v175 offset:22528
	ds_read_b128 v[210:213], v175 offset:23552
	global_load_lds_dwordx4 v146, s[8:9]
	s_mov_b32 m0, s51
	s_nop 0
	global_load_lds_dwordx4 v150, s[8:9]
	s_barrier
	s_waitcnt lgkmcnt(0)
	v_mfma_f32_16x16x32_bf16 v[62:65], v[130:133], v[180:183], 0
	v_mfma_f32_16x16x32_bf16 v[58:61], v[138:141], v[180:183], 0
	v_mfma_f32_16x16x32_bf16 v[54:57], v[130:133], v[190:193], 0
	v_mfma_f32_16x16x32_bf16 v[46:49], v[138:141], v[190:193], 0
	v_mfma_f32_16x16x32_bf16 v[38:41], v[130:133], v[198:201], 0
	v_mfma_f32_16x16x32_bf16 v[30:33], v[138:141], v[198:201], 0
	v_mfma_f32_16x16x32_bf16 v[22:25], v[130:133], v[206:209], 0
	v_mfma_f32_16x16x32_bf16 v[14:17], v[138:141], v[206:209], 0
	v_mfma_f32_16x16x32_bf16 v[62:65], v[134:137], v[184:187], v[62:65]
	v_mfma_f32_16x16x32_bf16 v[58:61], v[142:145], v[184:187], v[58:61]
	v_mfma_f32_16x16x32_bf16 v[54:57], v[134:137], v[194:197], v[54:57]
	v_mfma_f32_16x16x32_bf16 v[46:49], v[142:145], v[194:197], v[46:49]
	v_mfma_f32_16x16x32_bf16 v[38:41], v[134:137], v[202:205], v[38:41]
	v_mfma_f32_16x16x32_bf16 v[30:33], v[142:145], v[202:205], v[30:33]
	v_mfma_f32_16x16x32_bf16 v[22:25], v[134:137], v[210:213], v[22:25]
	v_mfma_f32_16x16x32_bf16 v[14:17], v[142:145], v[210:213], v[14:17]
	s_barrier
	s_add_u32 s74, s6, 0x40000
	s_addc_u32 s75, s7, 0
	s_add_i32 s76, s67, s49
	s_mov_b32 m0, s76
	s_nop 0
	global_load_lds_dwordx4 v148, s[74:75]
	s_add_i32 m0, s76, 0x2000
	s_nop 0
	global_load_lds_dwordx4 v152, s[74:75]
	s_waitcnt vmcnt(6)
	s_barrier
	v_mfma_f32_16x16x32_bf16 v[50:53], v[214:217], v[180:183], 0
	v_mfma_f32_16x16x32_bf16 v[42:45], v[222:225], v[180:183], 0
	v_mfma_f32_16x16x32_bf16 v[34:37], v[214:217], v[190:193], 0
	v_mfma_f32_16x16x32_bf16 v[26:29], v[222:225], v[190:193], 0
	v_mfma_f32_16x16x32_bf16 v[18:21], v[214:217], v[198:201], 0
	v_mfma_f32_16x16x32_bf16 v[10:13], v[222:225], v[198:201], 0
	v_mfma_f32_16x16x32_bf16 v[6:9], v[214:217], v[206:209], 0
	v_mfma_f32_16x16x32_bf16 v[2:5], v[222:225], v[206:209], 0
	v_mfma_f32_16x16x32_bf16 v[50:53], v[218:221], v[184:187], v[50:53]
	v_mfma_f32_16x16x32_bf16 v[42:45], v[226:229], v[184:187], v[42:45]
	v_mfma_f32_16x16x32_bf16 v[34:37], v[218:221], v[194:197], v[34:37]
	v_mfma_f32_16x16x32_bf16 v[26:29], v[226:229], v[194:197], v[26:29]
	v_mfma_f32_16x16x32_bf16 v[18:21], v[218:221], v[202:205], v[18:21]
	v_mfma_f32_16x16x32_bf16 v[10:13], v[226:229], v[202:205], v[10:13]
	v_mfma_f32_16x16x32_bf16 v[6:9], v[218:221], v[210:213], v[6:9]
	v_mfma_f32_16x16x32_bf16 v[2:5], v[226:229], v[210:213], v[2:5]
	s_add_i32 s74, 0, 0x18000
	v_add_u32_e32 v142, s74, v171
	s_barrier
	ds_read_b128 v[130:133], v142
	ds_read_b128 v[134:137], v142 offset:1024
	ds_read_b128 v[138:141], v142 offset:2048
	ds_read_b128 v[142:145], v142 offset:3072
	s_add_u32 s8, s8, 0x40000
	s_addc_u32 s9, s9, 0
	s_mov_b32 m0, s52
	ds_read_b128 v[180:183], v175 offset:32768
	ds_read_b128 v[184:187], v175 offset:33792
	ds_read_b128 v[190:193], v175 offset:34816
	ds_read_b128 v[194:197], v175 offset:35840
	ds_read_b128 v[198:201], v175 offset:36864
	ds_read_b128 v[202:205], v175 offset:37888
	ds_read_b128 v[206:209], v175 offset:38912
	ds_read_b128 v[210:213], v175 offset:39936
	global_load_lds_dwordx4 v146, s[8:9]
	s_mov_b32 m0, s53
	s_nop 0
	global_load_lds_dwordx4 v150, s[8:9]
	s_waitcnt lgkmcnt(8)
	s_barrier
	s_waitcnt lgkmcnt(0)
	v_mfma_f32_16x16x32_bf16 v[126:129], v[130:133], v[180:183], v[126:129]
	v_mfma_f32_16x16x32_bf16 v[122:125], v[138:141], v[180:183], v[122:125]
	v_mfma_f32_16x16x32_bf16 v[118:121], v[130:133], v[190:193], v[118:121]
	v_mfma_f32_16x16x32_bf16 v[110:113], v[138:141], v[190:193], v[110:113]
	v_mfma_f32_16x16x32_bf16 v[102:105], v[130:133], v[198:201], v[102:105]
	v_mfma_f32_16x16x32_bf16 v[94:97], v[138:141], v[198:201], v[94:97]
	v_mfma_f32_16x16x32_bf16 v[86:89], v[130:133], v[206:209], v[86:89]
	v_mfma_f32_16x16x32_bf16 v[78:81], v[138:141], v[206:209], v[78:81]
	v_mfma_f32_16x16x32_bf16 v[126:129], v[134:137], v[184:187], v[126:129]
	v_mfma_f32_16x16x32_bf16 v[122:125], v[142:145], v[184:187], v[122:125]
	v_mfma_f32_16x16x32_bf16 v[118:121], v[134:137], v[194:197], v[118:121]
	v_mfma_f32_16x16x32_bf16 v[110:113], v[142:145], v[194:197], v[110:113]
	v_mfma_f32_16x16x32_bf16 v[102:105], v[134:137], v[202:205], v[102:105]
	v_mfma_f32_16x16x32_bf16 v[94:97], v[142:145], v[202:205], v[94:97]
	v_mfma_f32_16x16x32_bf16 v[86:89], v[134:137], v[210:213], v[86:89]
	v_mfma_f32_16x16x32_bf16 v[78:81], v[142:145], v[210:213], v[78:81]
	s_barrier
	s_add_i32 s8, 0, 0x1c000
	s_add_i32 s9, s74, s49
	v_add_u32_e32 v154, s8, v171
	s_mov_b32 m0, s9
	ds_read_b128 v[214:217], v154
	ds_read_b128 v[218:221], v154 offset:1024
	ds_read_b128 v[222:225], v154 offset:2048
	ds_read_b128 v[226:229], v154 offset:3072
	global_load_lds_dwordx4 v148, s[98:99]
	s_add_i32 m0, s9, 0x2000
	s_nop 0
	global_load_lds_dwordx4 v152, s[98:99]
	s_barrier
	s_waitcnt lgkmcnt(0)
	v_mfma_f32_16x16x32_bf16 v[114:117], v[214:217], v[180:183], v[114:117]
	v_mfma_f32_16x16x32_bf16 v[106:109], v[222:225], v[180:183], v[106:109]
	v_mfma_f32_16x16x32_bf16 v[98:101], v[214:217], v[190:193], v[98:101]
	v_mfma_f32_16x16x32_bf16 v[90:93], v[222:225], v[190:193], v[90:93]
	v_mfma_f32_16x16x32_bf16 v[82:85], v[214:217], v[198:201], v[82:85]
	v_mfma_f32_16x16x32_bf16 v[74:77], v[222:225], v[198:201], v[74:77]
	v_mfma_f32_16x16x32_bf16 v[70:73], v[214:217], v[206:209], v[70:73]
	v_mfma_f32_16x16x32_bf16 v[66:69], v[222:225], v[206:209], v[66:69]
	v_mfma_f32_16x16x32_bf16 v[114:117], v[218:221], v[184:187], v[114:117]
	v_mfma_f32_16x16x32_bf16 v[106:109], v[226:229], v[184:187], v[106:109]
	v_mfma_f32_16x16x32_bf16 v[98:101], v[218:221], v[194:197], v[98:101]
	v_mfma_f32_16x16x32_bf16 v[90:93], v[226:229], v[194:197], v[90:93]
	v_mfma_f32_16x16x32_bf16 v[82:85], v[218:221], v[202:205], v[82:85]
	v_mfma_f32_16x16x32_bf16 v[74:77], v[226:229], v[202:205], v[74:77]
	v_mfma_f32_16x16x32_bf16 v[70:73], v[218:221], v[210:213], v[70:73]
	v_mfma_f32_16x16x32_bf16 v[66:69], v[226:229], v[210:213], v[66:69]
	s_mov_b32 m0, s56
	s_barrier
	ds_read_b128 v[180:183], v175 offset:49152
	ds_read_b128 v[184:187], v175 offset:50176
	ds_read_b128 v[190:193], v175 offset:51200
	ds_read_b128 v[194:197], v175 offset:52224
	ds_read_b128 v[198:201], v175 offset:53248
	ds_read_b128 v[202:205], v175 offset:54272
	ds_read_b128 v[206:209], v175 offset:55296
	ds_read_b128 v[210:213], v175 offset:56320
	global_load_lds_dwordx4 v146, s[100:101]
	s_mov_b32 m0, s57
	s_nop 0
	global_load_lds_dwordx4 v150, s[100:101]
	s_barrier
	s_waitcnt lgkmcnt(0)
	v_mfma_f32_16x16x32_bf16 v[62:65], v[130:133], v[180:183], v[62:65]
	v_mfma_f32_16x16x32_bf16 v[58:61], v[138:141], v[180:183], v[58:61]
	v_mfma_f32_16x16x32_bf16 v[54:57], v[130:133], v[190:193], v[54:57]
	v_mfma_f32_16x16x32_bf16 v[46:49], v[138:141], v[190:193], v[46:49]
	v_mfma_f32_16x16x32_bf16 v[38:41], v[130:133], v[198:201], v[38:41]
	v_mfma_f32_16x16x32_bf16 v[30:33], v[138:141], v[198:201], v[30:33]
	v_mfma_f32_16x16x32_bf16 v[22:25], v[130:133], v[206:209], v[22:25]
	v_mfma_f32_16x16x32_bf16 v[14:17], v[138:141], v[206:209], v[14:17]
	v_mfma_f32_16x16x32_bf16 v[62:65], v[134:137], v[184:187], v[62:65]
	v_mfma_f32_16x16x32_bf16 v[58:61], v[142:145], v[184:187], v[58:61]
	v_mfma_f32_16x16x32_bf16 v[54:57], v[134:137], v[194:197], v[54:57]
	v_mfma_f32_16x16x32_bf16 v[46:49], v[142:145], v[194:197], v[46:49]
	v_mfma_f32_16x16x32_bf16 v[38:41], v[134:137], v[202:205], v[38:41]
	v_mfma_f32_16x16x32_bf16 v[30:33], v[142:145], v[202:205], v[30:33]
	v_mfma_f32_16x16x32_bf16 v[22:25], v[134:137], v[210:213], v[22:25]
	v_mfma_f32_16x16x32_bf16 v[14:17], v[142:145], v[210:213], v[14:17]
	s_barrier
	s_add_u32 s6, s6, 0x40080
	s_addc_u32 s7, s7, 0
	s_add_i32 s8, s8, s49
	s_mov_b32 m0, s8
	s_nop 0
	global_load_lds_dwordx4 v148, s[6:7]
	s_add_i32 m0, s8, 0x2000
	s_nop 0
	global_load_lds_dwordx4 v152, s[6:7]
	s_waitcnt vmcnt(6)
	s_barrier
	v_mfma_f32_16x16x32_bf16 v[50:53], v[214:217], v[180:183], v[50:53]
	v_mfma_f32_16x16x32_bf16 v[42:45], v[222:225], v[180:183], v[42:45]
	v_mfma_f32_16x16x32_bf16 v[34:37], v[214:217], v[190:193], v[34:37]
	v_mfma_f32_16x16x32_bf16 v[26:29], v[222:225], v[190:193], v[26:29]
	v_mfma_f32_16x16x32_bf16 v[18:21], v[214:217], v[198:201], v[18:21]
	v_mfma_f32_16x16x32_bf16 v[10:13], v[222:225], v[198:201], v[10:13]
	v_mfma_f32_16x16x32_bf16 v[6:9], v[214:217], v[206:209], v[6:9]
	v_mfma_f32_16x16x32_bf16 v[2:5], v[222:225], v[206:209], v[2:5]
	v_mfma_f32_16x16x32_bf16 v[50:53], v[218:221], v[184:187], v[50:53]
	v_mfma_f32_16x16x32_bf16 v[42:45], v[226:229], v[184:187], v[42:45]
	v_mfma_f32_16x16x32_bf16 v[34:37], v[218:221], v[194:197], v[34:37]
	v_mfma_f32_16x16x32_bf16 v[26:29], v[226:229], v[194:197], v[26:29]
	v_mfma_f32_16x16x32_bf16 v[18:21], v[218:221], v[202:205], v[18:21]
	v_mfma_f32_16x16x32_bf16 v[10:13], v[226:229], v[202:205], v[10:13]
	v_mfma_f32_16x16x32_bf16 v[6:9], v[218:221], v[210:213], v[6:9]
	v_mfma_f32_16x16x32_bf16 v[2:5], v[226:229], v[210:213], v[2:5]
	s_add_i32 s73, s73, 2
	s_add_u32 s2, s2, 0x100
	s_addc_u32 s3, s3, 0
	s_add_u32 s71, s71, 0x100
	s_addc_u32 s72, s72, 0
	s_cmp_gt_u32 s73, 13
	s_barrier
	s_cbranch_scc1 .Lpeel_p1_exit
.LBB0_212:
	ds_read_b128 v[130:133], v173
	ds_read_b128 v[134:137], v173 offset:1024
	ds_read_b128 v[138:141], v173 offset:2048
	ds_read_b128 v[142:145], v173 offset:3072
	s_add_u32 s6, s2, 0xfffc0080
	s_addc_u32 s7, s3, -1
	s_cmp_eq_u32 s73, 12
	s_cselect_b32 s9, s1, s7
	s_cselect_b32 s8, s33, s6
	s_cselect_b32 s7, s39, s72
	s_cselect_b32 s6, s41, s71
	s_add_i32 m0, s50, 0xc000
	ds_read_b128 v[180:183], v175
	ds_read_b128 v[184:187], v175 offset:1024
	ds_read_b128 v[190:193], v175 offset:2048
	ds_read_b128 v[194:197], v175 offset:3072
	ds_read_b128 v[198:201], v175 offset:4096
	ds_read_b128 v[202:205], v175 offset:5120
	ds_read_b128 v[206:209], v175 offset:6144
	ds_read_b128 v[210:213], v175 offset:7168
	global_load_lds_dwordx4 v156, s[2:3]
	s_add_i32 m0, s50, 0xe000
	s_nop 0
	global_load_lds_dwordx4 v158, s[2:3]
	s_waitcnt lgkmcnt(8)
	s_barrier
	s_waitcnt lgkmcnt(0)
	v_mfma_f32_16x16x32_bf16 v[126:129], v[130:133], v[180:183], v[126:129]
	v_mfma_f32_16x16x32_bf16 v[122:125], v[138:141], v[180:183], v[122:125]
	v_mfma_f32_16x16x32_bf16 v[118:121], v[130:133], v[190:193], v[118:121]
	v_mfma_f32_16x16x32_bf16 v[110:113], v[138:141], v[190:193], v[110:113]
	v_mfma_f32_16x16x32_bf16 v[102:105], v[130:133], v[198:201], v[102:105]
	v_mfma_f32_16x16x32_bf16 v[94:97], v[138:141], v[198:201], v[94:97]
	v_mfma_f32_16x16x32_bf16 v[86:89], v[130:133], v[206:209], v[86:89]
	v_mfma_f32_16x16x32_bf16 v[78:81], v[138:141], v[206:209], v[78:81]
	v_mfma_f32_16x16x32_bf16 v[126:129], v[134:137], v[184:187], v[126:129]
	v_mfma_f32_16x16x32_bf16 v[122:125], v[142:145], v[184:187], v[122:125]
	v_mfma_f32_16x16x32_bf16 v[118:121], v[134:137], v[194:197], v[118:121]
	v_mfma_f32_16x16x32_bf16 v[110:113], v[142:145], v[194:197], v[110:113]
	v_mfma_f32_16x16x32_bf16 v[102:105], v[134:137], v[202:205], v[102:105]
	v_mfma_f32_16x16x32_bf16 v[94:97], v[142:145], v[202:205], v[94:97]
	v_mfma_f32_16x16x32_bf16 v[86:89], v[134:137], v[210:213], v[86:89]
	v_mfma_f32_16x16x32_bf16 v[78:81], v[142:145], v[210:213], v[78:81]
	s_barrier
	s_add_i32 s74, s66, s49
	s_add_u32 s98, s6, 0x80
	s_addc_u32 s99, s7, 0
	s_mov_b32 m0, s74
	ds_read_b128 v[214:217], v177
	ds_read_b128 v[218:221], v177 offset:1024
	ds_read_b128 v[222:225], v177 offset:2048
	ds_read_b128 v[226:229], v177 offset:3072
	global_load_lds_dwordx4 v148, s[6:7]
	s_add_i32 m0, s74, 0x2000
	s_nop 0
	global_load_lds_dwordx4 v152, s[6:7]
	s_barrier
	s_waitcnt lgkmcnt(0)
	v_mfma_f32_16x16x32_bf16 v[114:117], v[214:217], v[180:183], v[114:117]
	v_mfma_f32_16x16x32_bf16 v[106:109], v[222:225], v[180:183], v[106:109]
	v_mfma_f32_16x16x32_bf16 v[98:101], v[214:217], v[190:193], v[98:101]
	v_mfma_f32_16x16x32_bf16 v[90:93], v[222:225], v[190:193], v[90:93]
	v_mfma_f32_16x16x32_bf16 v[82:85], v[214:217], v[198:201], v[82:85]
	v_mfma_f32_16x16x32_bf16 v[74:77], v[222:225], v[198:201], v[74:77]
	v_mfma_f32_16x16x32_bf16 v[70:73], v[214:217], v[206:209], v[70:73]
	v_mfma_f32_16x16x32_bf16 v[66:69], v[222:225], v[206:209], v[66:69]
	v_mfma_f32_16x16x32_bf16 v[114:117], v[218:221], v[184:187], v[114:117]
	v_mfma_f32_16x16x32_bf16 v[106:109], v[226:229], v[184:187], v[106:109]
	v_mfma_f32_16x16x32_bf16 v[98:101], v[218:221], v[194:197], v[98:101]
	v_mfma_f32_16x16x32_bf16 v[90:93], v[226:229], v[194:197], v[90:93]
	v_mfma_f32_16x16x32_bf16 v[82:85], v[218:221], v[202:205], v[82:85]
	v_mfma_f32_16x16x32_bf16 v[74:77], v[226:229], v[202:205], v[74:77]
	v_mfma_f32_16x16x32_bf16 v[70:73], v[218:221], v[210:213], v[70:73]
	v_mfma_f32_16x16x32_bf16 v[66:69], v[226:229], v[210:213], v[66:69]
	s_mov_b32 m0, s50
	s_add_u32 s100, s8, 0x80
	s_addc_u32 s101, s9, 0
	s_barrier
	ds_read_b128 v[180:183], v175 offset:16384
	ds_read_b128 v[184:187], v175 offset:17408
	ds_read_b128 v[190:193], v175 offset:18432
	ds_read_b128 v[194:197], v175 offset:19456
	ds_read_b128 v[198:201], v175 offset:20480
	ds_read_b128 v[202:205], v175 offset:21504
	ds_read_b128 v[206:209], v175 offset:22528
	ds_read_b128 v[210:213], v175 offset:23552
	global_load_lds_dwordx4 v146, s[8:9]
	s_mov_b32 m0, s51
	s_nop 0
	global_load_lds_dwordx4 v150, s[8:9]
	s_barrier
	s_waitcnt lgkmcnt(0)
	v_mfma_f32_16x16x32_bf16 v[62:65], v[130:133], v[180:183], v[62:65]
	v_mfma_f32_16x16x32_bf16 v[58:61], v[138:141], v[180:183], v[58:61]
	v_mfma_f32_16x16x32_bf16 v[54:57], v[130:133], v[190:193], v[54:57]
	v_mfma_f32_16x16x32_bf16 v[46:49], v[138:141], v[190:193], v[46:49]
	v_mfma_f32_16x16x32_bf16 v[38:41], v[130:133], v[198:201], v[38:41]
	v_mfma_f32_16x16x32_bf16 v[30:33], v[138:141], v[198:201], v[30:33]
	v_mfma_f32_16x16x32_bf16 v[22:25], v[130:133], v[206:209], v[22:25]
	v_mfma_f32_16x16x32_bf16 v[14:17], v[138:141], v[206:209], v[14:17]
	v_mfma_f32_16x16x32_bf16 v[62:65], v[134:137], v[184:187], v[62:65]
	v_mfma_f32_16x16x32_bf16 v[58:61], v[142:145], v[184:187], v[58:61]
	v_mfma_f32_16x16x32_bf16 v[54:57], v[134:137], v[194:197], v[54:57]
	v_mfma_f32_16x16x32_bf16 v[46:49], v[142:145], v[194:197], v[46:49]
	v_mfma_f32_16x16x32_bf16 v[38:41], v[134:137], v[202:205], v[38:41]
	v_mfma_f32_16x16x32_bf16 v[30:33], v[142:145], v[202:205], v[30:33]
	v_mfma_f32_16x16x32_bf16 v[22:25], v[134:137], v[210:213], v[22:25]
	v_mfma_f32_16x16x32_bf16 v[14:17], v[142:145], v[210:213], v[14:17]
	s_barrier
	s_add_u32 s74, s6, 0x40000
	s_addc_u32 s75, s7, 0
	s_add_i32 s76, s67, s49
	s_mov_b32 m0, s76
	s_nop 0
	global_load_lds_dwordx4 v148, s[74:75]
	s_add_i32 m0, s76, 0x2000
	s_nop 0
	global_load_lds_dwordx4 v152, s[74:75]
	s_waitcnt vmcnt(6)
	s_barrier
	v_mfma_f32_16x16x32_bf16 v[50:53], v[214:217], v[180:183], v[50:53]
	v_mfma_f32_16x16x32_bf16 v[42:45], v[222:225], v[180:183], v[42:45]
	v_mfma_f32_16x16x32_bf16 v[34:37], v[214:217], v[190:193], v[34:37]
	v_mfma_f32_16x16x32_bf16 v[26:29], v[222:225], v[190:193], v[26:29]
	v_mfma_f32_16x16x32_bf16 v[18:21], v[214:217], v[198:201], v[18:21]
	v_mfma_f32_16x16x32_bf16 v[10:13], v[222:225], v[198:201], v[10:13]
	v_mfma_f32_16x16x32_bf16 v[6:9], v[214:217], v[206:209], v[6:9]
	v_mfma_f32_16x16x32_bf16 v[2:5], v[222:225], v[206:209], v[2:5]
	v_mfma_f32_16x16x32_bf16 v[50:53], v[218:221], v[184:187], v[50:53]
	v_mfma_f32_16x16x32_bf16 v[42:45], v[226:229], v[184:187], v[42:45]
	v_mfma_f32_16x16x32_bf16 v[34:37], v[218:221], v[194:197], v[34:37]
	v_mfma_f32_16x16x32_bf16 v[26:29], v[226:229], v[194:197], v[26:29]
	v_mfma_f32_16x16x32_bf16 v[18:21], v[218:221], v[202:205], v[18:21]
	v_mfma_f32_16x16x32_bf16 v[10:13], v[226:229], v[202:205], v[10:13]
	v_mfma_f32_16x16x32_bf16 v[6:9], v[218:221], v[210:213], v[6:9]
	v_mfma_f32_16x16x32_bf16 v[2:5], v[226:229], v[210:213], v[2:5]
	s_add_i32 s74, 0, 0x18000
	v_add_u32_e32 v142, s74, v171
	s_barrier
	ds_read_b128 v[130:133], v142
	ds_read_b128 v[134:137], v142 offset:1024
	ds_read_b128 v[138:141], v142 offset:2048
	ds_read_b128 v[142:145], v142 offset:3072
	s_add_u32 s8, s8, 0x40000
	s_addc_u32 s9, s9, 0
	s_mov_b32 m0, s52
	ds_read_b128 v[180:183], v175 offset:32768
	ds_read_b128 v[184:187], v175 offset:33792
	ds_read_b128 v[190:193], v175 offset:34816
	ds_read_b128 v[194:197], v175 offset:35840
	ds_read_b128 v[198:201], v175 offset:36864
	ds_read_b128 v[202:205], v175 offset:37888
	ds_read_b128 v[206:209], v175 offset:38912
	ds_read_b128 v[210:213], v175 offset:39936
	global_load_lds_dwordx4 v146, s[8:9]
	s_mov_b32 m0, s53
	s_nop 0
	global_load_lds_dwordx4 v150, s[8:9]
	s_waitcnt lgkmcnt(8)
	s_barrier
	s_waitcnt lgkmcnt(0)
	v_mfma_f32_16x16x32_bf16 v[126:129], v[130:133], v[180:183], v[126:129]
	v_mfma_f32_16x16x32_bf16 v[122:125], v[138:141], v[180:183], v[122:125]
	v_mfma_f32_16x16x32_bf16 v[118:121], v[130:133], v[190:193], v[118:121]
	v_mfma_f32_16x16x32_bf16 v[110:113], v[138:141], v[190:193], v[110:113]
	v_mfma_f32_16x16x32_bf16 v[102:105], v[130:133], v[198:201], v[102:105]
	v_mfma_f32_16x16x32_bf16 v[94:97], v[138:141], v[198:201], v[94:97]
	v_mfma_f32_16x16x32_bf16 v[86:89], v[130:133], v[206:209], v[86:89]
	v_mfma_f32_16x16x32_bf16 v[78:81], v[138:141], v[206:209], v[78:81]
	v_mfma_f32_16x16x32_bf16 v[126:129], v[134:137], v[184:187], v[126:129]
	v_mfma_f32_16x16x32_bf16 v[122:125], v[142:145], v[184:187], v[122:125]
	v_mfma_f32_16x16x32_bf16 v[118:121], v[134:137], v[194:197], v[118:121]
	v_mfma_f32_16x16x32_bf16 v[110:113], v[142:145], v[194:197], v[110:113]
	v_mfma_f32_16x16x32_bf16 v[102:105], v[134:137], v[202:205], v[102:105]
	v_mfma_f32_16x16x32_bf16 v[94:97], v[142:145], v[202:205], v[94:97]
	v_mfma_f32_16x16x32_bf16 v[86:89], v[134:137], v[210:213], v[86:89]
	v_mfma_f32_16x16x32_bf16 v[78:81], v[142:145], v[210:213], v[78:81]
	s_barrier
	s_add_i32 s8, 0, 0x1c000
	s_add_i32 s9, s74, s49
	v_add_u32_e32 v154, s8, v171
	s_mov_b32 m0, s9
	ds_read_b128 v[214:217], v154
	ds_read_b128 v[218:221], v154 offset:1024
	ds_read_b128 v[222:225], v154 offset:2048
	ds_read_b128 v[226:229], v154 offset:3072
	global_load_lds_dwordx4 v148, s[98:99]
	s_add_i32 m0, s9, 0x2000
	s_nop 0
	global_load_lds_dwordx4 v152, s[98:99]
	s_barrier
	s_waitcnt lgkmcnt(0)
	v_mfma_f32_16x16x32_bf16 v[114:117], v[214:217], v[180:183], v[114:117]
	v_mfma_f32_16x16x32_bf16 v[106:109], v[222:225], v[180:183], v[106:109]
	v_mfma_f32_16x16x32_bf16 v[98:101], v[214:217], v[190:193], v[98:101]
	v_mfma_f32_16x16x32_bf16 v[90:93], v[222:225], v[190:193], v[90:93]
	v_mfma_f32_16x16x32_bf16 v[82:85], v[214:217], v[198:201], v[82:85]
	v_mfma_f32_16x16x32_bf16 v[74:77], v[222:225], v[198:201], v[74:77]
	v_mfma_f32_16x16x32_bf16 v[70:73], v[214:217], v[206:209], v[70:73]
	v_mfma_f32_16x16x32_bf16 v[66:69], v[222:225], v[206:209], v[66:69]
	v_mfma_f32_16x16x32_bf16 v[114:117], v[218:221], v[184:187], v[114:117]
	v_mfma_f32_16x16x32_bf16 v[106:109], v[226:229], v[184:187], v[106:109]
	v_mfma_f32_16x16x32_bf16 v[98:101], v[218:221], v[194:197], v[98:101]
	v_mfma_f32_16x16x32_bf16 v[90:93], v[226:229], v[194:197], v[90:93]
	v_mfma_f32_16x16x32_bf16 v[82:85], v[218:221], v[202:205], v[82:85]
	v_mfma_f32_16x16x32_bf16 v[74:77], v[226:229], v[202:205], v[74:77]
	v_mfma_f32_16x16x32_bf16 v[70:73], v[218:221], v[210:213], v[70:73]
	v_mfma_f32_16x16x32_bf16 v[66:69], v[226:229], v[210:213], v[66:69]
	s_mov_b32 m0, s56
	s_barrier
	ds_read_b128 v[180:183], v175 offset:49152
	ds_read_b128 v[184:187], v175 offset:50176
	ds_read_b128 v[190:193], v175 offset:51200
	ds_read_b128 v[194:197], v175 offset:52224
	ds_read_b128 v[198:201], v175 offset:53248
	ds_read_b128 v[202:205], v175 offset:54272
	ds_read_b128 v[206:209], v175 offset:55296
	ds_read_b128 v[210:213], v175 offset:56320
	global_load_lds_dwordx4 v146, s[100:101]
	s_mov_b32 m0, s57
	s_nop 0
	global_load_lds_dwordx4 v150, s[100:101]
	s_barrier
	s_waitcnt lgkmcnt(0)
	v_mfma_f32_16x16x32_bf16 v[62:65], v[130:133], v[180:183], v[62:65]
	v_mfma_f32_16x16x32_bf16 v[58:61], v[138:141], v[180:183], v[58:61]
	v_mfma_f32_16x16x32_bf16 v[54:57], v[130:133], v[190:193], v[54:57]
	v_mfma_f32_16x16x32_bf16 v[46:49], v[138:141], v[190:193], v[46:49]
	v_mfma_f32_16x16x32_bf16 v[38:41], v[130:133], v[198:201], v[38:41]
	v_mfma_f32_16x16x32_bf16 v[30:33], v[138:141], v[198:201], v[30:33]
	v_mfma_f32_16x16x32_bf16 v[22:25], v[130:133], v[206:209], v[22:25]
	v_mfma_f32_16x16x32_bf16 v[14:17], v[138:141], v[206:209], v[14:17]
	v_mfma_f32_16x16x32_bf16 v[62:65], v[134:137], v[184:187], v[62:65]
	v_mfma_f32_16x16x32_bf16 v[58:61], v[142:145], v[184:187], v[58:61]
	v_mfma_f32_16x16x32_bf16 v[54:57], v[134:137], v[194:197], v[54:57]
	v_mfma_f32_16x16x32_bf16 v[46:49], v[142:145], v[194:197], v[46:49]
	v_mfma_f32_16x16x32_bf16 v[38:41], v[134:137], v[202:205], v[38:41]
	v_mfma_f32_16x16x32_bf16 v[30:33], v[142:145], v[202:205], v[30:33]
	v_mfma_f32_16x16x32_bf16 v[22:25], v[134:137], v[210:213], v[22:25]
	v_mfma_f32_16x16x32_bf16 v[14:17], v[142:145], v[210:213], v[14:17]
	s_barrier
	s_add_u32 s6, s6, 0x40080
	s_addc_u32 s7, s7, 0
	s_add_i32 s8, s8, s49
	s_mov_b32 m0, s8
	s_nop 0
	global_load_lds_dwordx4 v148, s[6:7]
	s_add_i32 m0, s8, 0x2000
	s_nop 0
	global_load_lds_dwordx4 v152, s[6:7]
	s_waitcnt vmcnt(6)
	s_barrier
	v_mfma_f32_16x16x32_bf16 v[50:53], v[214:217], v[180:183], v[50:53]
	v_mfma_f32_16x16x32_bf16 v[42:45], v[222:225], v[180:183], v[42:45]
	v_mfma_f32_16x16x32_bf16 v[34:37], v[214:217], v[190:193], v[34:37]
	v_mfma_f32_16x16x32_bf16 v[26:29], v[222:225], v[190:193], v[26:29]
	v_mfma_f32_16x16x32_bf16 v[18:21], v[214:217], v[198:201], v[18:21]
	v_mfma_f32_16x16x32_bf16 v[10:13], v[222:225], v[198:201], v[10:13]
	v_mfma_f32_16x16x32_bf16 v[6:9], v[214:217], v[206:209], v[6:9]
	v_mfma_f32_16x16x32_bf16 v[2:5], v[222:225], v[206:209], v[2:5]
	v_mfma_f32_16x16x32_bf16 v[50:53], v[218:221], v[184:187], v[50:53]
	v_mfma_f32_16x16x32_bf16 v[42:45], v[226:229], v[184:187], v[42:45]
	v_mfma_f32_16x16x32_bf16 v[34:37], v[218:221], v[194:197], v[34:37]
	v_mfma_f32_16x16x32_bf16 v[26:29], v[226:229], v[194:197], v[26:29]
	v_mfma_f32_16x16x32_bf16 v[18:21], v[218:221], v[202:205], v[18:21]
	v_mfma_f32_16x16x32_bf16 v[10:13], v[226:229], v[202:205], v[10:13]
	v_mfma_f32_16x16x32_bf16 v[6:9], v[218:221], v[210:213], v[6:9]
	v_mfma_f32_16x16x32_bf16 v[2:5], v[226:229], v[210:213], v[2:5]
	s_add_i32 s73, s73, 2
	s_add_u32 s2, s2, 0x100
	s_addc_u32 s3, s3, 0
	s_add_u32 s71, s71, 0x100
	s_addc_u32 s72, s72, 0
	s_cmp_gt_u32 s73, 13
	s_barrier
	s_cbranch_scc0 .LBB0_212

.Lpeel_p8:
	ds_read_b128 v[130:133], v181
	ds_read_b128 v[134:137], v181 offset:1024
	ds_read_b128 v[138:141], v181 offset:2048
	ds_read_b128 v[142:145], v181 offset:3072
	s_add_u32 s2, s0, 0xfffc0080
	s_addc_u32 s3, s1, -1
	s_cmp_eq_u32 s74, 12
	s_cselect_b32 s45, s33, s3
	s_cselect_b32 s44, s39, s2
	s_cselect_b32 s3, s37, s73
	s_cselect_b32 s2, s71, s72
	s_add_i32 m0, s52, 0xc000
	ds_read_b128 v[146:149], v183
	ds_read_b128 v[150:153], v183 offset:1024
	ds_read_b128 v[154:157], v183 offset:2048
	ds_read_b128 v[158:161], v183 offset:3072
	ds_read_b128 v[162:165], v183 offset:4096
	ds_read_b128 v[166:169], v183 offset:5120
	ds_read_b128 v[170:173], v183 offset:6144
	ds_read_b128 v[174:177], v183 offset:7168
	global_load_lds_dwordx4 v192, s[0:1]
	s_add_i32 m0, s52, 0xe000
	s_nop 0
	global_load_lds_dwordx4 v194, s[0:1]
	s_waitcnt lgkmcnt(8)
	s_barrier
	s_waitcnt lgkmcnt(0)
	v_mfma_f32_16x16x32_bf16 v[62:65], v[130:133], v[146:149], 0
	v_mfma_f32_16x16x32_bf16 v[30:33], v[138:141], v[146:149], 0
	v_mfma_f32_16x16x32_bf16 v[54:57], v[130:133], v[154:157], 0
	v_mfma_f32_16x16x32_bf16 v[22:25], v[138:141], v[154:157], 0
	v_mfma_f32_16x16x32_bf16 v[46:49], v[130:133], v[162:165], 0
	v_mfma_f32_16x16x32_bf16 v[14:17], v[138:141], v[162:165], 0
	v_mfma_f32_16x16x32_bf16 v[38:41], v[130:133], v[170:173], 0
	v_mfma_f32_16x16x32_bf16 v[6:9], v[138:141], v[170:173], 0
	v_mfma_f32_16x16x32_bf16 v[62:65], v[134:137], v[150:153], v[62:65]
	v_mfma_f32_16x16x32_bf16 v[30:33], v[142:145], v[150:153], v[30:33]
	v_mfma_f32_16x16x32_bf16 v[54:57], v[134:137], v[158:161], v[54:57]
	v_mfma_f32_16x16x32_bf16 v[22:25], v[142:145], v[158:161], v[22:25]
	v_mfma_f32_16x16x32_bf16 v[46:49], v[134:137], v[166:169], v[46:49]
	v_mfma_f32_16x16x32_bf16 v[14:17], v[142:145], v[166:169], v[14:17]
	v_mfma_f32_16x16x32_bf16 v[38:41], v[134:137], v[174:177], v[38:41]
	v_mfma_f32_16x16x32_bf16 v[6:9], v[142:145], v[174:177], v[6:9]
	s_barrier
	s_add_i32 s75, s66, s51
	s_add_u32 s98, s2, 0x80
	s_addc_u32 s99, s3, 0
	s_mov_b32 m0, s75
	ds_read_b128 v[200:203], v206
	ds_read_b128 v[212:215], v206 offset:1024
	ds_read_b128 v[216:219], v206 offset:2048
	ds_read_b128 v[220:223], v206 offset:3072
	global_load_lds_dwordx4 v186, s[2:3]
	s_add_i32 m0, s75, 0x2000
	s_nop 0
	global_load_lds_dwordx4 v190, s[2:3]
	s_barrier
	s_waitcnt lgkmcnt(0)
	v_mfma_f32_16x16x32_bf16 v[58:61], v[200:203], v[146:149], 0
	v_mfma_f32_16x16x32_bf16 v[26:29], v[216:219], v[146:149], 0
	v_mfma_f32_16x16x32_bf16 v[50:53], v[200:203], v[154:157], 0
	v_mfma_f32_16x16x32_bf16 v[18:21], v[216:219], v[154:157], 0
	v_mfma_f32_16x16x32_bf16 v[42:45], v[200:203], v[162:165], 0
	v_mfma_f32_16x16x32_bf16 v[10:13], v[216:219], v[162:165], 0
	v_mfma_f32_16x16x32_bf16 v[34:37], v[200:203], v[170:173], 0
	v_mfma_f32_16x16x32_bf16 v[2:5], v[216:219], v[170:173], 0
	v_mfma_f32_16x16x32_bf16 v[58:61], v[212:215], v[150:153], v[58:61]
	v_mfma_f32_16x16x32_bf16 v[26:29], v[220:223], v[150:153], v[26:29]
	v_mfma_f32_16x16x32_bf16 v[50:53], v[212:215], v[158:161], v[50:53]
	v_mfma_f32_16x16x32_bf16 v[18:21], v[220:223], v[158:161], v[18:21]
	v_mfma_f32_16x16x32_bf16 v[42:45], v[212:215], v[166:169], v[42:45]
	v_mfma_f32_16x16x32_bf16 v[10:13], v[220:223], v[166:169], v[10:13]
	v_mfma_f32_16x16x32_bf16 v[34:37], v[212:215], v[174:177], v[34:37]
	v_mfma_f32_16x16x32_bf16 v[2:5], v[220:223], v[174:177], v[2:5]
	s_mov_b32 m0, s52
	s_add_u32 s100, s44, 0x80
	s_addc_u32 s101, s45, 0
	s_barrier
	ds_read_b128 v[146:149], v183 offset:16384
	ds_read_b128 v[150:153], v183 offset:17408
	ds_read_b128 v[154:157], v183 offset:18432
	ds_read_b128 v[158:161], v183 offset:19456
	ds_read_b128 v[162:165], v183 offset:20480
	ds_read_b128 v[166:169], v183 offset:21504
	ds_read_b128 v[170:173], v183 offset:22528
	ds_read_b128 v[174:177], v183 offset:23552
	global_load_lds_dwordx4 v184, s[44:45]
	s_mov_b32 m0, s53
	s_nop 0
	global_load_lds_dwordx4 v188, s[44:45]
	s_barrier
	s_waitcnt lgkmcnt(0)
	v_mfma_f32_16x16x32_bf16 v[126:129], v[130:133], v[146:149], 0
	v_mfma_f32_16x16x32_bf16 v[102:105], v[138:141], v[146:149], 0
	v_mfma_f32_16x16x32_bf16 v[122:125], v[130:133], v[154:157], 0
	v_mfma_f32_16x16x32_bf16 v[90:93], v[138:141], v[154:157], 0
	v_mfma_f32_16x16x32_bf16 v[118:121], v[130:133], v[162:165], 0
	v_mfma_f32_16x16x32_bf16 v[78:81], v[138:141], v[162:165], 0
	v_mfma_f32_16x16x32_bf16 v[106:109], v[130:133], v[170:173], 0
	v_mfma_f32_16x16x32_bf16 v[70:73], v[138:141], v[170:173], 0
	v_mfma_f32_16x16x32_bf16 v[126:129], v[134:137], v[150:153], v[126:129]
	v_mfma_f32_16x16x32_bf16 v[102:105], v[142:145], v[150:153], v[102:105]
	v_mfma_f32_16x16x32_bf16 v[122:125], v[134:137], v[158:161], v[122:125]
	v_mfma_f32_16x16x32_bf16 v[90:93], v[142:145], v[158:161], v[90:93]
	v_mfma_f32_16x16x32_bf16 v[118:121], v[134:137], v[166:169], v[118:121]
	v_mfma_f32_16x16x32_bf16 v[78:81], v[142:145], v[166:169], v[78:81]
	v_mfma_f32_16x16x32_bf16 v[106:109], v[134:137], v[174:177], v[106:109]
	v_mfma_f32_16x16x32_bf16 v[70:73], v[142:145], v[174:177], v[70:73]
	s_barrier
	s_add_u32 s76, s2, 0x40000
	s_addc_u32 s77, s3, 0
	s_add_i32 s75, s67, s51
	s_mov_b32 m0, s75
	s_nop 0
	global_load_lds_dwordx4 v186, s[76:77]
	s_add_i32 m0, s75, 0x2000
	s_nop 0
	global_load_lds_dwordx4 v190, s[76:77]
	s_waitcnt vmcnt(6)
	s_barrier
	v_mfma_f32_16x16x32_bf16 v[114:117], v[200:203], v[146:149], 0
	v_mfma_f32_16x16x32_bf16 v[86:89], v[216:219], v[146:149], 0
	v_mfma_f32_16x16x32_bf16 v[110:113], v[200:203], v[154:157], 0
	v_mfma_f32_16x16x32_bf16 v[82:85], v[216:219], v[154:157], 0
	v_mfma_f32_16x16x32_bf16 v[98:101], v[200:203], v[162:165], 0
	v_mfma_f32_16x16x32_bf16 v[74:77], v[216:219], v[162:165], 0
	v_mfma_f32_16x16x32_bf16 v[94:97], v[200:203], v[170:173], 0
	v_mfma_f32_16x16x32_bf16 v[66:69], v[216:219], v[170:173], 0
	v_mfma_f32_16x16x32_bf16 v[114:117], v[212:215], v[150:153], v[114:117]
	v_mfma_f32_16x16x32_bf16 v[86:89], v[220:223], v[150:153], v[86:89]
	v_mfma_f32_16x16x32_bf16 v[110:113], v[212:215], v[158:161], v[110:113]
	v_mfma_f32_16x16x32_bf16 v[82:85], v[220:223], v[158:161], v[82:85]
	v_mfma_f32_16x16x32_bf16 v[98:101], v[212:215], v[166:169], v[98:101]
	v_mfma_f32_16x16x32_bf16 v[74:77], v[220:223], v[166:169], v[74:77]
	v_mfma_f32_16x16x32_bf16 v[94:97], v[212:215], v[174:177], v[94:97]
	v_mfma_f32_16x16x32_bf16 v[66:69], v[220:223], v[174:177], v[66:69]
	s_add_i32 s75, 0, 0x18000
	v_add_u32_e32 v142, s75, v1
	s_barrier
	ds_read_b128 v[130:133], v142
	ds_read_b128 v[134:137], v142 offset:1024
	ds_read_b128 v[138:141], v142 offset:2048
	ds_read_b128 v[142:145], v142 offset:3072
	s_add_u32 s44, s44, 0x40000
	s_addc_u32 s45, s45, 0
	s_mov_b32 m0, s54
	ds_read_b128 v[146:149], v183 offset:32768
	ds_read_b128 v[150:153], v183 offset:33792
	ds_read_b128 v[154:157], v183 offset:34816
	ds_read_b128 v[158:161], v183 offset:35840
	ds_read_b128 v[162:165], v183 offset:36864
	ds_read_b128 v[166:169], v183 offset:37888
	ds_read_b128 v[170:173], v183 offset:38912
	ds_read_b128 v[174:177], v183 offset:39936
	global_load_lds_dwordx4 v184, s[44:45]
	s_mov_b32 m0, s55
	s_nop 0
	global_load_lds_dwordx4 v188, s[44:45]
	s_waitcnt lgkmcnt(8)
	s_barrier
	s_waitcnt lgkmcnt(0)
	v_mfma_f32_16x16x32_bf16 v[62:65], v[130:133], v[146:149], v[62:65]
	v_mfma_f32_16x16x32_bf16 v[30:33], v[138:141], v[146:149], v[30:33]
	v_mfma_f32_16x16x32_bf16 v[54:57], v[130:133], v[154:157], v[54:57]
	v_mfma_f32_16x16x32_bf16 v[22:25], v[138:141], v[154:157], v[22:25]
	v_mfma_f32_16x16x32_bf16 v[46:49], v[130:133], v[162:165], v[46:49]
	v_mfma_f32_16x16x32_bf16 v[14:17], v[138:141], v[162:165], v[14:17]
	v_mfma_f32_16x16x32_bf16 v[38:41], v[130:133], v[170:173], v[38:41]
	v_mfma_f32_16x16x32_bf16 v[6:9], v[138:141], v[170:173], v[6:9]
	v_mfma_f32_16x16x32_bf16 v[62:65], v[134:137], v[150:153], v[62:65]
	v_mfma_f32_16x16x32_bf16 v[30:33], v[142:145], v[150:153], v[30:33]
	v_mfma_f32_16x16x32_bf16 v[54:57], v[134:137], v[158:161], v[54:57]
	v_mfma_f32_16x16x32_bf16 v[22:25], v[142:145], v[158:161], v[22:25]
	v_mfma_f32_16x16x32_bf16 v[46:49], v[134:137], v[166:169], v[46:49]
	v_mfma_f32_16x16x32_bf16 v[14:17], v[142:145], v[166:169], v[14:17]
	v_mfma_f32_16x16x32_bf16 v[38:41], v[134:137], v[174:177], v[38:41]
	v_mfma_f32_16x16x32_bf16 v[6:9], v[142:145], v[174:177], v[6:9]
	s_barrier
	s_add_i32 s44, 0, 0x1c000
	s_add_i32 s45, s75, s51
	v_add_u32_e32 v207, s44, v1
	s_mov_b32 m0, s45
	ds_read_b128 v[200:203], v207
	ds_read_b128 v[212:215], v207 offset:1024
	ds_read_b128 v[216:219], v207 offset:2048
	ds_read_b128 v[220:223], v207 offset:3072
	global_load_lds_dwordx4 v186, s[98:99]
	s_add_i32 m0, s45, 0x2000
	s_nop 0
	global_load_lds_dwordx4 v190, s[98:99]
	s_barrier
	s_waitcnt lgkmcnt(0)
	v_mfma_f32_16x16x32_bf16 v[58:61], v[200:203], v[146:149], v[58:61]
	v_mfma_f32_16x16x32_bf16 v[26:29], v[216:219], v[146:149], v[26:29]
	v_mfma_f32_16x16x32_bf16 v[50:53], v[200:203], v[154:157], v[50:53]
	v_mfma_f32_16x16x32_bf16 v[18:21], v[216:219], v[154:157], v[18:21]
	v_mfma_f32_16x16x32_bf16 v[42:45], v[200:203], v[162:165], v[42:45]
	v_mfma_f32_16x16x32_bf16 v[10:13], v[216:219], v[162:165], v[10:13]
	v_mfma_f32_16x16x32_bf16 v[34:37], v[200:203], v[170:173], v[34:37]
	v_mfma_f32_16x16x32_bf16 v[2:5], v[216:219], v[170:173], v[2:5]
	v_mfma_f32_16x16x32_bf16 v[58:61], v[212:215], v[150:153], v[58:61]
	v_mfma_f32_16x16x32_bf16 v[26:29], v[220:223], v[150:153], v[26:29]
	v_mfma_f32_16x16x32_bf16 v[50:53], v[212:215], v[158:161], v[50:53]
	v_mfma_f32_16x16x32_bf16 v[18:21], v[220:223], v[158:161], v[18:21]
	v_mfma_f32_16x16x32_bf16 v[42:45], v[212:215], v[166:169], v[42:45]
	v_mfma_f32_16x16x32_bf16 v[10:13], v[220:223], v[166:169], v[10:13]
	v_mfma_f32_16x16x32_bf16 v[34:37], v[212:215], v[174:177], v[34:37]
	v_mfma_f32_16x16x32_bf16 v[2:5], v[220:223], v[174:177], v[2:5]
	s_mov_b32 m0, s59
	s_barrier
	ds_read_b128 v[146:149], v183 offset:49152
	ds_read_b128 v[150:153], v183 offset:50176
	ds_read_b128 v[154:157], v183 offset:51200
	ds_read_b128 v[158:161], v183 offset:52224
	ds_read_b128 v[162:165], v183 offset:53248
	ds_read_b128 v[166:169], v183 offset:54272
	ds_read_b128 v[170:173], v183 offset:55296
	ds_read_b128 v[174:177], v183 offset:56320
	global_load_lds_dwordx4 v184, s[100:101]
	s_mov_b32 m0, s60
	s_nop 0
	global_load_lds_dwordx4 v188, s[100:101]
	s_barrier
	s_waitcnt lgkmcnt(0)
	v_mfma_f32_16x16x32_bf16 v[126:129], v[130:133], v[146:149], v[126:129]
	v_mfma_f32_16x16x32_bf16 v[102:105], v[138:141], v[146:149], v[102:105]
	v_mfma_f32_16x16x32_bf16 v[122:125], v[130:133], v[154:157], v[122:125]
	v_mfma_f32_16x16x32_bf16 v[90:93], v[138:141], v[154:157], v[90:93]
	v_mfma_f32_16x16x32_bf16 v[118:121], v[130:133], v[162:165], v[118:121]
	v_mfma_f32_16x16x32_bf16 v[78:81], v[138:141], v[162:165], v[78:81]
	v_mfma_f32_16x16x32_bf16 v[106:109], v[130:133], v[170:173], v[106:109]
	v_mfma_f32_16x16x32_bf16 v[70:73], v[138:141], v[170:173], v[70:73]
	v_mfma_f32_16x16x32_bf16 v[126:129], v[134:137], v[150:153], v[126:129]
	v_mfma_f32_16x16x32_bf16 v[102:105], v[142:145], v[150:153], v[102:105]
	v_mfma_f32_16x16x32_bf16 v[122:125], v[134:137], v[158:161], v[122:125]
	v_mfma_f32_16x16x32_bf16 v[90:93], v[142:145], v[158:161], v[90:93]
	v_mfma_f32_16x16x32_bf16 v[118:121], v[134:137], v[166:169], v[118:121]
	v_mfma_f32_16x16x32_bf16 v[78:81], v[142:145], v[166:169], v[78:81]
	v_mfma_f32_16x16x32_bf16 v[106:109], v[134:137], v[174:177], v[106:109]
	v_mfma_f32_16x16x32_bf16 v[70:73], v[142:145], v[174:177], v[70:73]
	s_barrier
	s_add_u32 s2, s2, 0x40080
	s_addc_u32 s3, s3, 0
	s_add_i32 s44, s44, s51
	s_mov_b32 m0, s44
	s_nop 0
	global_load_lds_dwordx4 v186, s[2:3]
	s_add_i32 m0, s44, 0x2000
	s_nop 0
	global_load_lds_dwordx4 v190, s[2:3]
	s_waitcnt vmcnt(6)
	s_barrier
	v_mfma_f32_16x16x32_bf16 v[114:117], v[200:203], v[146:149], v[114:117]
	v_mfma_f32_16x16x32_bf16 v[86:89], v[216:219], v[146:149], v[86:89]
	v_mfma_f32_16x16x32_bf16 v[110:113], v[200:203], v[154:157], v[110:113]
	v_mfma_f32_16x16x32_bf16 v[82:85], v[216:219], v[154:157], v[82:85]
	v_mfma_f32_16x16x32_bf16 v[98:101], v[200:203], v[162:165], v[98:101]
	v_mfma_f32_16x16x32_bf16 v[74:77], v[216:219], v[162:165], v[74:77]
	v_mfma_f32_16x16x32_bf16 v[94:97], v[200:203], v[170:173], v[94:97]
	v_mfma_f32_16x16x32_bf16 v[66:69], v[216:219], v[170:173], v[66:69]
	v_mfma_f32_16x16x32_bf16 v[114:117], v[212:215], v[150:153], v[114:117]
	v_mfma_f32_16x16x32_bf16 v[86:89], v[220:223], v[150:153], v[86:89]
	v_mfma_f32_16x16x32_bf16 v[110:113], v[212:215], v[158:161], v[110:113]
	v_mfma_f32_16x16x32_bf16 v[82:85], v[220:223], v[158:161], v[82:85]
	v_mfma_f32_16x16x32_bf16 v[98:101], v[212:215], v[166:169], v[98:101]
	v_mfma_f32_16x16x32_bf16 v[74:77], v[220:223], v[166:169], v[74:77]
	v_mfma_f32_16x16x32_bf16 v[94:97], v[212:215], v[174:177], v[94:97]
	v_mfma_f32_16x16x32_bf16 v[66:69], v[220:223], v[174:177], v[66:69]
	s_add_i32 s74, s74, 2
	s_add_u32 s0, s0, 0x100
	s_addc_u32 s1, s1, 0
	s_add_u32 s72, s72, 0x100
	s_addc_u32 s73, s73, 0
	s_cmp_gt_u32 s74, 13
	s_barrier
	s_cbranch_scc1 .Lpeel_p8_exit
.LBB0_1090:
	ds_read_b128 v[130:133], v181
	ds_read_b128 v[134:137], v181 offset:1024
	ds_read_b128 v[138:141], v181 offset:2048
	ds_read_b128 v[142:145], v181 offset:3072
	s_add_u32 s2, s0, 0xfffc0080
	s_addc_u32 s3, s1, -1
	s_cmp_eq_u32 s74, 12
	s_cselect_b32 s45, s33, s3
	s_cselect_b32 s44, s39, s2
	s_cselect_b32 s3, s37, s73
	s_cselect_b32 s2, s71, s72
	s_add_i32 m0, s52, 0xc000
	ds_read_b128 v[146:149], v183
	ds_read_b128 v[150:153], v183 offset:1024
	ds_read_b128 v[154:157], v183 offset:2048
	ds_read_b128 v[158:161], v183 offset:3072
	ds_read_b128 v[162:165], v183 offset:4096
	ds_read_b128 v[166:169], v183 offset:5120
	ds_read_b128 v[170:173], v183 offset:6144
	ds_read_b128 v[174:177], v183 offset:7168
	global_load_lds_dwordx4 v192, s[0:1]
	s_add_i32 m0, s52, 0xe000
	s_nop 0
	global_load_lds_dwordx4 v194, s[0:1]
	s_waitcnt lgkmcnt(8)
	s_barrier
	s_waitcnt lgkmcnt(0)
	v_mfma_f32_16x16x32_bf16 v[62:65], v[130:133], v[146:149], v[62:65]
	v_mfma_f32_16x16x32_bf16 v[30:33], v[138:141], v[146:149], v[30:33]
	v_mfma_f32_16x16x32_bf16 v[54:57], v[130:133], v[154:157], v[54:57]
	v_mfma_f32_16x16x32_bf16 v[22:25], v[138:141], v[154:157], v[22:25]
	v_mfma_f32_16x16x32_bf16 v[46:49], v[130:133], v[162:165], v[46:49]
	v_mfma_f32_16x16x32_bf16 v[14:17], v[138:141], v[162:165], v[14:17]
	v_mfma_f32_16x16x32_bf16 v[38:41], v[130:133], v[170:173], v[38:41]
	v_mfma_f32_16x16x32_bf16 v[6:9], v[138:141], v[170:173], v[6:9]
	v_mfma_f32_16x16x32_bf16 v[62:65], v[134:137], v[150:153], v[62:65]
	v_mfma_f32_16x16x32_bf16 v[30:33], v[142:145], v[150:153], v[30:33]
	v_mfma_f32_16x16x32_bf16 v[54:57], v[134:137], v[158:161], v[54:57]
	v_mfma_f32_16x16x32_bf16 v[22:25], v[142:145], v[158:161], v[22:25]
	v_mfma_f32_16x16x32_bf16 v[46:49], v[134:137], v[166:169], v[46:49]
	v_mfma_f32_16x16x32_bf16 v[14:17], v[142:145], v[166:169], v[14:17]
	v_mfma_f32_16x16x32_bf16 v[38:41], v[134:137], v[174:177], v[38:41]
	v_mfma_f32_16x16x32_bf16 v[6:9], v[142:145], v[174:177], v[6:9]
	s_barrier
	s_add_i32 s75, s66, s51
	s_add_u32 s98, s2, 0x80
	s_addc_u32 s99, s3, 0
	s_mov_b32 m0, s75
	ds_read_b128 v[200:203], v206
	ds_read_b128 v[212:215], v206 offset:1024
	ds_read_b128 v[216:219], v206 offset:2048
	ds_read_b128 v[220:223], v206 offset:3072
	global_load_lds_dwordx4 v186, s[2:3]
	s_add_i32 m0, s75, 0x2000
	s_nop 0
	global_load_lds_dwordx4 v190, s[2:3]
	s_barrier
	s_waitcnt lgkmcnt(0)
	v_mfma_f32_16x16x32_bf16 v[58:61], v[200:203], v[146:149], v[58:61]
	v_mfma_f32_16x16x32_bf16 v[26:29], v[216:219], v[146:149], v[26:29]
	v_mfma_f32_16x16x32_bf16 v[50:53], v[200:203], v[154:157], v[50:53]
	v_mfma_f32_16x16x32_bf16 v[18:21], v[216:219], v[154:157], v[18:21]
	v_mfma_f32_16x16x32_bf16 v[42:45], v[200:203], v[162:165], v[42:45]
	v_mfma_f32_16x16x32_bf16 v[10:13], v[216:219], v[162:165], v[10:13]
	v_mfma_f32_16x16x32_bf16 v[34:37], v[200:203], v[170:173], v[34:37]
	v_mfma_f32_16x16x32_bf16 v[2:5], v[216:219], v[170:173], v[2:5]
	v_mfma_f32_16x16x32_bf16 v[58:61], v[212:215], v[150:153], v[58:61]
	v_mfma_f32_16x16x32_bf16 v[26:29], v[220:223], v[150:153], v[26:29]
	v_mfma_f32_16x16x32_bf16 v[50:53], v[212:215], v[158:161], v[50:53]
	v_mfma_f32_16x16x32_bf16 v[18:21], v[220:223], v[158:161], v[18:21]
	v_mfma_f32_16x16x32_bf16 v[42:45], v[212:215], v[166:169], v[42:45]
	v_mfma_f32_16x16x32_bf16 v[10:13], v[220:223], v[166:169], v[10:13]
	v_mfma_f32_16x16x32_bf16 v[34:37], v[212:215], v[174:177], v[34:37]
	v_mfma_f32_16x16x32_bf16 v[2:5], v[220:223], v[174:177], v[2:5]
	s_mov_b32 m0, s52
	s_add_u32 s100, s44, 0x80
	s_addc_u32 s101, s45, 0
	s_barrier
	ds_read_b128 v[146:149], v183 offset:16384
	ds_read_b128 v[150:153], v183 offset:17408
	ds_read_b128 v[154:157], v183 offset:18432
	ds_read_b128 v[158:161], v183 offset:19456
	ds_read_b128 v[162:165], v183 offset:20480
	ds_read_b128 v[166:169], v183 offset:21504
	ds_read_b128 v[170:173], v183 offset:22528
	ds_read_b128 v[174:177], v183 offset:23552
	global_load_lds_dwordx4 v184, s[44:45]
	s_mov_b32 m0, s53
	s_nop 0
	global_load_lds_dwordx4 v188, s[44:45]
	s_barrier
	s_waitcnt lgkmcnt(0)
	v_mfma_f32_16x16x32_bf16 v[126:129], v[130:133], v[146:149], v[126:129]
	v_mfma_f32_16x16x32_bf16 v[102:105], v[138:141], v[146:149], v[102:105]
	v_mfma_f32_16x16x32_bf16 v[122:125], v[130:133], v[154:157], v[122:125]
	v_mfma_f32_16x16x32_bf16 v[90:93], v[138:141], v[154:157], v[90:93]
	v_mfma_f32_16x16x32_bf16 v[118:121], v[130:133], v[162:165], v[118:121]
	v_mfma_f32_16x16x32_bf16 v[78:81], v[138:141], v[162:165], v[78:81]
	v_mfma_f32_16x16x32_bf16 v[106:109], v[130:133], v[170:173], v[106:109]
	v_mfma_f32_16x16x32_bf16 v[70:73], v[138:141], v[170:173], v[70:73]
	v_mfma_f32_16x16x32_bf16 v[126:129], v[134:137], v[150:153], v[126:129]
	v_mfma_f32_16x16x32_bf16 v[102:105], v[142:145], v[150:153], v[102:105]
	v_mfma_f32_16x16x32_bf16 v[122:125], v[134:137], v[158:161], v[122:125]
	v_mfma_f32_16x16x32_bf16 v[90:93], v[142:145], v[158:161], v[90:93]
	v_mfma_f32_16x16x32_bf16 v[118:121], v[134:137], v[166:169], v[118:121]
	v_mfma_f32_16x16x32_bf16 v[78:81], v[142:145], v[166:169], v[78:81]
	v_mfma_f32_16x16x32_bf16 v[106:109], v[134:137], v[174:177], v[106:109]
	v_mfma_f32_16x16x32_bf16 v[70:73], v[142:145], v[174:177], v[70:73]
	s_barrier
	s_add_u32 s76, s2, 0x40000
	s_addc_u32 s77, s3, 0
	s_add_i32 s75, s67, s51
	s_mov_b32 m0, s75
	s_nop 0
	global_load_lds_dwordx4 v186, s[76:77]
	s_add_i32 m0, s75, 0x2000
	s_nop 0
	global_load_lds_dwordx4 v190, s[76:77]
	s_waitcnt vmcnt(6)
	s_barrier
	v_mfma_f32_16x16x32_bf16 v[114:117], v[200:203], v[146:149], v[114:117]
	v_mfma_f32_16x16x32_bf16 v[86:89], v[216:219], v[146:149], v[86:89]
	v_mfma_f32_16x16x32_bf16 v[110:113], v[200:203], v[154:157], v[110:113]
	v_mfma_f32_16x16x32_bf16 v[82:85], v[216:219], v[154:157], v[82:85]
	v_mfma_f32_16x16x32_bf16 v[98:101], v[200:203], v[162:165], v[98:101]
	v_mfma_f32_16x16x32_bf16 v[74:77], v[216:219], v[162:165], v[74:77]
	v_mfma_f32_16x16x32_bf16 v[94:97], v[200:203], v[170:173], v[94:97]
	v_mfma_f32_16x16x32_bf16 v[66:69], v[216:219], v[170:173], v[66:69]
	v_mfma_f32_16x16x32_bf16 v[114:117], v[212:215], v[150:153], v[114:117]
	v_mfma_f32_16x16x32_bf16 v[86:89], v[220:223], v[150:153], v[86:89]
	v_mfma_f32_16x16x32_bf16 v[110:113], v[212:215], v[158:161], v[110:113]
	v_mfma_f32_16x16x32_bf16 v[82:85], v[220:223], v[158:161], v[82:85]
	v_mfma_f32_16x16x32_bf16 v[98:101], v[212:215], v[166:169], v[98:101]
	v_mfma_f32_16x16x32_bf16 v[74:77], v[220:223], v[166:169], v[74:77]
	v_mfma_f32_16x16x32_bf16 v[94:97], v[212:215], v[174:177], v[94:97]
	v_mfma_f32_16x16x32_bf16 v[66:69], v[220:223], v[174:177], v[66:69]
	s_add_i32 s75, 0, 0x18000
	v_add_u32_e32 v142, s75, v1
	s_barrier
	ds_read_b128 v[130:133], v142
	ds_read_b128 v[134:137], v142 offset:1024
	ds_read_b128 v[138:141], v142 offset:2048
	ds_read_b128 v[142:145], v142 offset:3072
	s_add_u32 s44, s44, 0x40000
	s_addc_u32 s45, s45, 0
	s_mov_b32 m0, s54
	ds_read_b128 v[146:149], v183 offset:32768
	ds_read_b128 v[150:153], v183 offset:33792
	ds_read_b128 v[154:157], v183 offset:34816
	ds_read_b128 v[158:161], v183 offset:35840
	ds_read_b128 v[162:165], v183 offset:36864
	ds_read_b128 v[166:169], v183 offset:37888
	ds_read_b128 v[170:173], v183 offset:38912
	ds_read_b128 v[174:177], v183 offset:39936
	global_load_lds_dwordx4 v184, s[44:45]
	s_mov_b32 m0, s55
	s_nop 0
	global_load_lds_dwordx4 v188, s[44:45]
	s_waitcnt lgkmcnt(8)
	s_barrier
	s_waitcnt lgkmcnt(0)
	v_mfma_f32_16x16x32_bf16 v[62:65], v[130:133], v[146:149], v[62:65]
	v_mfma_f32_16x16x32_bf16 v[30:33], v[138:141], v[146:149], v[30:33]
	v_mfma_f32_16x16x32_bf16 v[54:57], v[130:133], v[154:157], v[54:57]
	v_mfma_f32_16x16x32_bf16 v[22:25], v[138:141], v[154:157], v[22:25]
	v_mfma_f32_16x16x32_bf16 v[46:49], v[130:133], v[162:165], v[46:49]
	v_mfma_f32_16x16x32_bf16 v[14:17], v[138:141], v[162:165], v[14:17]
	v_mfma_f32_16x16x32_bf16 v[38:41], v[130:133], v[170:173], v[38:41]
	v_mfma_f32_16x16x32_bf16 v[6:9], v[138:141], v[170:173], v[6:9]
	v_mfma_f32_16x16x32_bf16 v[62:65], v[134:137], v[150:153], v[62:65]
	v_mfma_f32_16x16x32_bf16 v[30:33], v[142:145], v[150:153], v[30:33]
	v_mfma_f32_16x16x32_bf16 v[54:57], v[134:137], v[158:161], v[54:57]
	v_mfma_f32_16x16x32_bf16 v[22:25], v[142:145], v[158:161], v[22:25]
	v_mfma_f32_16x16x32_bf16 v[46:49], v[134:137], v[166:169], v[46:49]
	v_mfma_f32_16x16x32_bf16 v[14:17], v[142:145], v[166:169], v[14:17]
	v_mfma_f32_16x16x32_bf16 v[38:41], v[134:137], v[174:177], v[38:41]
	v_mfma_f32_16x16x32_bf16 v[6:9], v[142:145], v[174:177], v[6:9]
	s_barrier
	s_add_i32 s44, 0, 0x1c000
	s_add_i32 s45, s75, s51
	v_add_u32_e32 v207, s44, v1
	s_mov_b32 m0, s45
	ds_read_b128 v[200:203], v207
	ds_read_b128 v[212:215], v207 offset:1024
	ds_read_b128 v[216:219], v207 offset:2048
	ds_read_b128 v[220:223], v207 offset:3072
	global_load_lds_dwordx4 v186, s[98:99]
	s_add_i32 m0, s45, 0x2000
	s_nop 0
	global_load_lds_dwordx4 v190, s[98:99]
	s_barrier
	s_waitcnt lgkmcnt(0)
	v_mfma_f32_16x16x32_bf16 v[58:61], v[200:203], v[146:149], v[58:61]
	v_mfma_f32_16x16x32_bf16 v[26:29], v[216:219], v[146:149], v[26:29]
	v_mfma_f32_16x16x32_bf16 v[50:53], v[200:203], v[154:157], v[50:53]
	v_mfma_f32_16x16x32_bf16 v[18:21], v[216:219], v[154:157], v[18:21]
	v_mfma_f32_16x16x32_bf16 v[42:45], v[200:203], v[162:165], v[42:45]
	v_mfma_f32_16x16x32_bf16 v[10:13], v[216:219], v[162:165], v[10:13]
	v_mfma_f32_16x16x32_bf16 v[34:37], v[200:203], v[170:173], v[34:37]
	v_mfma_f32_16x16x32_bf16 v[2:5], v[216:219], v[170:173], v[2:5]
	v_mfma_f32_16x16x32_bf16 v[58:61], v[212:215], v[150:153], v[58:61]
	v_mfma_f32_16x16x32_bf16 v[26:29], v[220:223], v[150:153], v[26:29]
	v_mfma_f32_16x16x32_bf16 v[50:53], v[212:215], v[158:161], v[50:53]
	v_mfma_f32_16x16x32_bf16 v[18:21], v[220:223], v[158:161], v[18:21]
	v_mfma_f32_16x16x32_bf16 v[42:45], v[212:215], v[166:169], v[42:45]
	v_mfma_f32_16x16x32_bf16 v[10:13], v[220:223], v[166:169], v[10:13]
	v_mfma_f32_16x16x32_bf16 v[34:37], v[212:215], v[174:177], v[34:37]
	v_mfma_f32_16x16x32_bf16 v[2:5], v[220:223], v[174:177], v[2:5]
	s_mov_b32 m0, s59
	s_barrier
	ds_read_b128 v[146:149], v183 offset:49152
	ds_read_b128 v[150:153], v183 offset:50176
	ds_read_b128 v[154:157], v183 offset:51200
	ds_read_b128 v[158:161], v183 offset:52224
	ds_read_b128 v[162:165], v183 offset:53248
	ds_read_b128 v[166:169], v183 offset:54272
	ds_read_b128 v[170:173], v183 offset:55296
	ds_read_b128 v[174:177], v183 offset:56320
	global_load_lds_dwordx4 v184, s[100:101]
	s_mov_b32 m0, s60
	s_nop 0
	global_load_lds_dwordx4 v188, s[100:101]
	s_barrier
	s_waitcnt lgkmcnt(0)
	v_mfma_f32_16x16x32_bf16 v[126:129], v[130:133], v[146:149], v[126:129]
	v_mfma_f32_16x16x32_bf16 v[102:105], v[138:141], v[146:149], v[102:105]
	v_mfma_f32_16x16x32_bf16 v[122:125], v[130:133], v[154:157], v[122:125]
	v_mfma_f32_16x16x32_bf16 v[90:93], v[138:141], v[154:157], v[90:93]
	v_mfma_f32_16x16x32_bf16 v[118:121], v[130:133], v[162:165], v[118:121]
	v_mfma_f32_16x16x32_bf16 v[78:81], v[138:141], v[162:165], v[78:81]
	v_mfma_f32_16x16x32_bf16 v[106:109], v[130:133], v[170:173], v[106:109]
	v_mfma_f32_16x16x32_bf16 v[70:73], v[138:141], v[170:173], v[70:73]
	v_mfma_f32_16x16x32_bf16 v[126:129], v[134:137], v[150:153], v[126:129]
	v_mfma_f32_16x16x32_bf16 v[102:105], v[142:145], v[150:153], v[102:105]
	v_mfma_f32_16x16x32_bf16 v[122:125], v[134:137], v[158:161], v[122:125]
	v_mfma_f32_16x16x32_bf16 v[90:93], v[142:145], v[158:161], v[90:93]
	v_mfma_f32_16x16x32_bf16 v[118:121], v[134:137], v[166:169], v[118:121]
	v_mfma_f32_16x16x32_bf16 v[78:81], v[142:145], v[166:169], v[78:81]
	v_mfma_f32_16x16x32_bf16 v[106:109], v[134:137], v[174:177], v[106:109]
	v_mfma_f32_16x16x32_bf16 v[70:73], v[142:145], v[174:177], v[70:73]
	s_barrier
	s_add_u32 s2, s2, 0x40080
	s_addc_u32 s3, s3, 0
	s_add_i32 s44, s44, s51
	s_mov_b32 m0, s44
	s_nop 0
	global_load_lds_dwordx4 v186, s[2:3]
	s_add_i32 m0, s44, 0x2000
	s_nop 0
	global_load_lds_dwordx4 v190, s[2:3]
	s_waitcnt vmcnt(6)
	s_barrier
	v_mfma_f32_16x16x32_bf16 v[114:117], v[200:203], v[146:149], v[114:117]
	v_mfma_f32_16x16x32_bf16 v[86:89], v[216:219], v[146:149], v[86:89]
	v_mfma_f32_16x16x32_bf16 v[110:113], v[200:203], v[154:157], v[110:113]
	v_mfma_f32_16x16x32_bf16 v[82:85], v[216:219], v[154:157], v[82:85]
	v_mfma_f32_16x16x32_bf16 v[98:101], v[200:203], v[162:165], v[98:101]
	v_mfma_f32_16x16x32_bf16 v[74:77], v[216:219], v[162:165], v[74:77]
	v_mfma_f32_16x16x32_bf16 v[94:97], v[200:203], v[170:173], v[94:97]
	v_mfma_f32_16x16x32_bf16 v[66:69], v[216:219], v[170:173], v[66:69]
	v_mfma_f32_16x16x32_bf16 v[114:117], v[212:215], v[150:153], v[114:117]
	v_mfma_f32_16x16x32_bf16 v[86:89], v[220:223], v[150:153], v[86:89]
	v_mfma_f32_16x16x32_bf16 v[110:113], v[212:215], v[158:161], v[110:113]
	v_mfma_f32_16x16x32_bf16 v[82:85], v[220:223], v[158:161], v[82:85]
	v_mfma_f32_16x16x32_bf16 v[98:101], v[212:215], v[166:169], v[98:101]
	v_mfma_f32_16x16x32_bf16 v[74:77], v[220:223], v[166:169], v[74:77]
	v_mfma_f32_16x16x32_bf16 v[94:97], v[212:215], v[174:177], v[94:97]
	v_mfma_f32_16x16x32_bf16 v[66:69], v[220:223], v[174:177], v[66:69]
	s_add_i32 s74, s74, 2
	s_add_u32 s0, s0, 0x100
	s_addc_u32 s1, s1, 0
	s_add_u32 s72, s72, 0x100
	s_addc_u32 s73, s73, 0
	s_cmp_gt_u32 s74, 13
	s_barrier
	s_cbranch_scc0 .LBB0_1090

.Lpeel_p10:
	ds_read_b128 v[152:155], v149
	ds_read_b128 v[156:159], v149 offset:1024
	ds_read_b128 v[160:163], v149 offset:2048
	ds_read_b128 v[164:167], v149 offset:3072
	s_add_u32 s18, s16, 0xfff50080
	s_addc_u32 s19, s17, -1
	s_cmp_eq_u32 s54, 40
	s_cselect_b32 s21, s3, s19
	s_cselect_b32 s20, s2, s18
	s_cselect_b32 s19, s5, s53
	s_cselect_b32 s18, s4, s52
	s_add_i32 m0, s30, 0xc000
	ds_read_b128 v[168:171], v150
	ds_read_b128 v[172:175], v150 offset:1024
	ds_read_b128 v[180:183], v150 offset:2048
	ds_read_b128 v[184:187], v150 offset:3072
	ds_read_b128 v[188:191], v150 offset:4096
	ds_read_b128 v[192:195], v150 offset:5120
	ds_read_b128 v[196:199], v150 offset:6144
	ds_read_b128 v[200:203], v150 offset:7168
	global_load_lds_dwordx4 v138, s[16:17]
	s_add_i32 m0, s30, 0xe000
	s_nop 0
	global_load_lds_dwordx4 v140, s[16:17]
	s_waitcnt lgkmcnt(8)
	s_barrier
	s_waitcnt lgkmcnt(0)
	v_mfma_f32_16x16x32_bf16 v[126:129], v[152:155], v[168:171], 0
	v_mfma_f32_16x16x32_bf16 v[122:125], v[160:163], v[168:171], 0
	v_mfma_f32_16x16x32_bf16 v[114:117], v[152:155], v[180:183], 0
	v_mfma_f32_16x16x32_bf16 v[106:109], v[160:163], v[180:183], 0
	v_mfma_f32_16x16x32_bf16 v[98:101], v[152:155], v[188:191], 0
	v_mfma_f32_16x16x32_bf16 v[90:93], v[160:163], v[188:191], 0
	v_mfma_f32_16x16x32_bf16 v[82:85], v[152:155], v[196:199], 0
	v_mfma_f32_16x16x32_bf16 v[74:77], v[160:163], v[196:199], 0
	v_mfma_f32_16x16x32_bf16 v[126:129], v[156:159], v[172:175], v[126:129]
	v_mfma_f32_16x16x32_bf16 v[122:125], v[164:167], v[172:175], v[122:125]
	v_mfma_f32_16x16x32_bf16 v[114:117], v[156:159], v[184:187], v[114:117]
	v_mfma_f32_16x16x32_bf16 v[106:109], v[164:167], v[184:187], v[106:109]
	v_mfma_f32_16x16x32_bf16 v[98:101], v[156:159], v[192:195], v[98:101]
	v_mfma_f32_16x16x32_bf16 v[90:93], v[164:167], v[192:195], v[90:93]
	v_mfma_f32_16x16x32_bf16 v[82:85], v[156:159], v[200:203], v[82:85]
	v_mfma_f32_16x16x32_bf16 v[74:77], v[164:167], v[200:203], v[74:77]
	s_barrier
	s_add_i32 s55, s41, s27
	s_add_u32 s98, s18, 0x80
	s_addc_u32 s99, s19, 0
	s_mov_b32 m0, s55
	ds_read_b128 v[206:209], v151
	ds_read_b128 v[212:215], v151 offset:1024
	ds_read_b128 v[216:219], v151 offset:2048
	ds_read_b128 v[220:223], v151 offset:3072
	global_load_lds_dwordx4 v134, s[18:19]
	s_add_i32 m0, s55, 0x2000
	s_nop 0
	global_load_lds_dwordx4 v136, s[18:19]
	s_barrier
	s_waitcnt lgkmcnt(0)
	v_mfma_f32_16x16x32_bf16 v[118:121], v[206:209], v[168:171], 0
	v_mfma_f32_16x16x32_bf16 v[110:113], v[216:219], v[168:171], 0
	v_mfma_f32_16x16x32_bf16 v[102:105], v[206:209], v[180:183], 0
	v_mfma_f32_16x16x32_bf16 v[94:97], v[216:219], v[180:183], 0
	v_mfma_f32_16x16x32_bf16 v[86:89], v[206:209], v[188:191], 0
	v_mfma_f32_16x16x32_bf16 v[78:81], v[216:219], v[188:191], 0
	v_mfma_f32_16x16x32_bf16 v[70:73], v[206:209], v[196:199], 0
	v_mfma_f32_16x16x32_bf16 v[66:69], v[216:219], v[196:199], 0
	v_mfma_f32_16x16x32_bf16 v[118:121], v[212:215], v[172:175], v[118:121]
	v_mfma_f32_16x16x32_bf16 v[110:113], v[220:223], v[172:175], v[110:113]
	v_mfma_f32_16x16x32_bf16 v[102:105], v[212:215], v[184:187], v[102:105]
	v_mfma_f32_16x16x32_bf16 v[94:97], v[220:223], v[184:187], v[94:97]
	v_mfma_f32_16x16x32_bf16 v[86:89], v[212:215], v[192:195], v[86:89]
	v_mfma_f32_16x16x32_bf16 v[78:81], v[220:223], v[192:195], v[78:81]
	v_mfma_f32_16x16x32_bf16 v[70:73], v[212:215], v[200:203], v[70:73]
	v_mfma_f32_16x16x32_bf16 v[66:69], v[220:223], v[200:203], v[66:69]
	s_mov_b32 m0, s30
	s_add_u32 s100, s20, 0x80
	s_addc_u32 s101, s21, 0
	s_barrier
	ds_read_b128 v[168:171], v150 offset:16384
	ds_read_b128 v[172:175], v150 offset:17408
	ds_read_b128 v[180:183], v150 offset:18432
	ds_read_b128 v[184:187], v150 offset:19456
	ds_read_b128 v[188:191], v150 offset:20480
	ds_read_b128 v[192:195], v150 offset:21504
	ds_read_b128 v[196:199], v150 offset:22528
	ds_read_b128 v[200:203], v150 offset:23552
	global_load_lds_dwordx4 v130, s[20:21]
	s_mov_b32 m0, s31
	s_nop 0
	global_load_lds_dwordx4 v132, s[20:21]
	s_barrier
	s_waitcnt lgkmcnt(0)
	v_mfma_f32_16x16x32_bf16 v[62:65], v[152:155], v[168:171], 0
	v_mfma_f32_16x16x32_bf16 v[58:61], v[160:163], v[168:171], 0
	v_mfma_f32_16x16x32_bf16 v[50:53], v[152:155], v[180:183], 0
	v_mfma_f32_16x16x32_bf16 v[42:45], v[160:163], v[180:183], 0
	v_mfma_f32_16x16x32_bf16 v[34:37], v[152:155], v[188:191], 0
	v_mfma_f32_16x16x32_bf16 v[26:29], v[160:163], v[188:191], 0
	v_mfma_f32_16x16x32_bf16 v[18:21], v[152:155], v[196:199], 0
	v_mfma_f32_16x16x32_bf16 v[10:13], v[160:163], v[196:199], 0
	v_mfma_f32_16x16x32_bf16 v[62:65], v[156:159], v[172:175], v[62:65]
	v_mfma_f32_16x16x32_bf16 v[58:61], v[164:167], v[172:175], v[58:61]
	v_mfma_f32_16x16x32_bf16 v[50:53], v[156:159], v[184:187], v[50:53]
	v_mfma_f32_16x16x32_bf16 v[42:45], v[164:167], v[184:187], v[42:45]
	v_mfma_f32_16x16x32_bf16 v[34:37], v[156:159], v[192:195], v[34:37]
	v_mfma_f32_16x16x32_bf16 v[26:29], v[164:167], v[192:195], v[26:29]
	v_mfma_f32_16x16x32_bf16 v[18:21], v[156:159], v[200:203], v[18:21]
	v_mfma_f32_16x16x32_bf16 v[10:13], v[164:167], v[200:203], v[10:13]
	s_barrier
	s_add_u32 s56, s18, 0xb0000
	s_addc_u32 s57, s19, 0
	s_add_i32 s55, s42, s27
	s_mov_b32 m0, s55
	s_nop 0
	global_load_lds_dwordx4 v134, s[56:57]
	s_add_i32 m0, s55, 0x2000
	s_nop 0
	global_load_lds_dwordx4 v136, s[56:57]
	s_waitcnt vmcnt(6)
	s_barrier
	v_mfma_f32_16x16x32_bf16 v[54:57], v[206:209], v[168:171], 0
	v_mfma_f32_16x16x32_bf16 v[46:49], v[216:219], v[168:171], 0
	v_mfma_f32_16x16x32_bf16 v[38:41], v[206:209], v[180:183], 0
	v_mfma_f32_16x16x32_bf16 v[30:33], v[216:219], v[180:183], 0
	v_mfma_f32_16x16x32_bf16 v[22:25], v[206:209], v[188:191], 0
	v_mfma_f32_16x16x32_bf16 v[14:17], v[216:219], v[188:191], 0
	v_mfma_f32_16x16x32_bf16 v[6:9], v[206:209], v[196:199], 0
	v_mfma_f32_16x16x32_bf16 v[2:5], v[216:219], v[196:199], 0
	v_mfma_f32_16x16x32_bf16 v[54:57], v[212:215], v[172:175], v[54:57]
	v_mfma_f32_16x16x32_bf16 v[46:49], v[220:223], v[172:175], v[46:49]
	v_mfma_f32_16x16x32_bf16 v[38:41], v[212:215], v[184:187], v[38:41]
	v_mfma_f32_16x16x32_bf16 v[30:33], v[220:223], v[184:187], v[30:33]
	v_mfma_f32_16x16x32_bf16 v[22:25], v[212:215], v[192:195], v[22:25]
	v_mfma_f32_16x16x32_bf16 v[14:17], v[220:223], v[192:195], v[14:17]
	v_mfma_f32_16x16x32_bf16 v[6:9], v[212:215], v[200:203], v[6:9]
	v_mfma_f32_16x16x32_bf16 v[2:5], v[220:223], v[200:203], v[2:5]
	s_add_i32 s55, 0, 0x18000
	v_add_u32_e32 v164, s55, v148
	s_barrier
	ds_read_b128 v[152:155], v164
	ds_read_b128 v[156:159], v164 offset:1024
	ds_read_b128 v[160:163], v164 offset:2048
	ds_read_b128 v[164:167], v164 offset:3072
	s_add_u32 s20, s20, 0xb0000
	s_addc_u32 s21, s21, 0
	s_mov_b32 m0, s33
	ds_read_b128 v[168:171], v150 offset:32768
	ds_read_b128 v[172:175], v150 offset:33792
	ds_read_b128 v[180:183], v150 offset:34816
	ds_read_b128 v[184:187], v150 offset:35840
	ds_read_b128 v[188:191], v150 offset:36864
	ds_read_b128 v[192:195], v150 offset:37888
	ds_read_b128 v[196:199], v150 offset:38912
	ds_read_b128 v[200:203], v150 offset:39936
	global_load_lds_dwordx4 v130, s[20:21]
	s_mov_b32 m0, s34
	s_nop 0
	global_load_lds_dwordx4 v132, s[20:21]
	s_waitcnt lgkmcnt(8)
	s_barrier
	s_waitcnt lgkmcnt(0)
	v_mfma_f32_16x16x32_bf16 v[126:129], v[152:155], v[168:171], v[126:129]
	v_mfma_f32_16x16x32_bf16 v[122:125], v[160:163], v[168:171], v[122:125]
	v_mfma_f32_16x16x32_bf16 v[114:117], v[152:155], v[180:183], v[114:117]
	v_mfma_f32_16x16x32_bf16 v[106:109], v[160:163], v[180:183], v[106:109]
	v_mfma_f32_16x16x32_bf16 v[98:101], v[152:155], v[188:191], v[98:101]
	v_mfma_f32_16x16x32_bf16 v[90:93], v[160:163], v[188:191], v[90:93]
	v_mfma_f32_16x16x32_bf16 v[82:85], v[152:155], v[196:199], v[82:85]
	v_mfma_f32_16x16x32_bf16 v[74:77], v[160:163], v[196:199], v[74:77]
	v_mfma_f32_16x16x32_bf16 v[126:129], v[156:159], v[172:175], v[126:129]
	v_mfma_f32_16x16x32_bf16 v[122:125], v[164:167], v[172:175], v[122:125]
	v_mfma_f32_16x16x32_bf16 v[114:117], v[156:159], v[184:187], v[114:117]
	v_mfma_f32_16x16x32_bf16 v[106:109], v[164:167], v[184:187], v[106:109]
	v_mfma_f32_16x16x32_bf16 v[98:101], v[156:159], v[192:195], v[98:101]
	v_mfma_f32_16x16x32_bf16 v[90:93], v[164:167], v[192:195], v[90:93]
	v_mfma_f32_16x16x32_bf16 v[82:85], v[156:159], v[200:203], v[82:85]
	v_mfma_f32_16x16x32_bf16 v[74:77], v[164:167], v[200:203], v[74:77]
	s_barrier
	s_add_i32 s20, 0, 0x1c000
	s_add_i32 s21, s55, s27
	v_add_u32_e32 v179, s20, v148
	s_mov_b32 m0, s21
	ds_read_b128 v[206:209], v179
	ds_read_b128 v[212:215], v179 offset:1024
	ds_read_b128 v[216:219], v179 offset:2048
	ds_read_b128 v[220:223], v179 offset:3072
	global_load_lds_dwordx4 v134, s[98:99]
	s_add_i32 m0, s21, 0x2000
	s_nop 0
	global_load_lds_dwordx4 v136, s[98:99]
	s_barrier
	s_waitcnt lgkmcnt(0)
	v_mfma_f32_16x16x32_bf16 v[118:121], v[206:209], v[168:171], v[118:121]
	v_mfma_f32_16x16x32_bf16 v[110:113], v[216:219], v[168:171], v[110:113]
	v_mfma_f32_16x16x32_bf16 v[102:105], v[206:209], v[180:183], v[102:105]
	v_mfma_f32_16x16x32_bf16 v[94:97], v[216:219], v[180:183], v[94:97]
	v_mfma_f32_16x16x32_bf16 v[86:89], v[206:209], v[188:191], v[86:89]
	v_mfma_f32_16x16x32_bf16 v[78:81], v[216:219], v[188:191], v[78:81]
	v_mfma_f32_16x16x32_bf16 v[70:73], v[206:209], v[196:199], v[70:73]
	v_mfma_f32_16x16x32_bf16 v[66:69], v[216:219], v[196:199], v[66:69]
	v_mfma_f32_16x16x32_bf16 v[118:121], v[212:215], v[172:175], v[118:121]
	v_mfma_f32_16x16x32_bf16 v[110:113], v[220:223], v[172:175], v[110:113]
	v_mfma_f32_16x16x32_bf16 v[102:105], v[212:215], v[184:187], v[102:105]
	v_mfma_f32_16x16x32_bf16 v[94:97], v[220:223], v[184:187], v[94:97]
	v_mfma_f32_16x16x32_bf16 v[86:89], v[212:215], v[192:195], v[86:89]
	v_mfma_f32_16x16x32_bf16 v[78:81], v[220:223], v[192:195], v[78:81]
	v_mfma_f32_16x16x32_bf16 v[70:73], v[212:215], v[200:203], v[70:73]
	v_mfma_f32_16x16x32_bf16 v[66:69], v[220:223], v[200:203], v[66:69]
	s_mov_b32 m0, s37
	s_barrier
	ds_read_b128 v[168:171], v150 offset:49152
	ds_read_b128 v[172:175], v150 offset:50176
	ds_read_b128 v[180:183], v150 offset:51200
	ds_read_b128 v[184:187], v150 offset:52224
	ds_read_b128 v[188:191], v150 offset:53248
	ds_read_b128 v[192:195], v150 offset:54272
	ds_read_b128 v[196:199], v150 offset:55296
	ds_read_b128 v[200:203], v150 offset:56320
	global_load_lds_dwordx4 v130, s[100:101]
	s_mov_b32 m0, s38
	s_nop 0
	global_load_lds_dwordx4 v132, s[100:101]
	s_barrier
	s_waitcnt lgkmcnt(0)
	v_mfma_f32_16x16x32_bf16 v[62:65], v[152:155], v[168:171], v[62:65]
	v_mfma_f32_16x16x32_bf16 v[58:61], v[160:163], v[168:171], v[58:61]
	v_mfma_f32_16x16x32_bf16 v[50:53], v[152:155], v[180:183], v[50:53]
	v_mfma_f32_16x16x32_bf16 v[42:45], v[160:163], v[180:183], v[42:45]
	v_mfma_f32_16x16x32_bf16 v[34:37], v[152:155], v[188:191], v[34:37]
	v_mfma_f32_16x16x32_bf16 v[26:29], v[160:163], v[188:191], v[26:29]
	v_mfma_f32_16x16x32_bf16 v[18:21], v[152:155], v[196:199], v[18:21]
	v_mfma_f32_16x16x32_bf16 v[10:13], v[160:163], v[196:199], v[10:13]
	v_mfma_f32_16x16x32_bf16 v[62:65], v[156:159], v[172:175], v[62:65]
	v_mfma_f32_16x16x32_bf16 v[58:61], v[164:167], v[172:175], v[58:61]
	v_mfma_f32_16x16x32_bf16 v[50:53], v[156:159], v[184:187], v[50:53]
	v_mfma_f32_16x16x32_bf16 v[42:45], v[164:167], v[184:187], v[42:45]
	v_mfma_f32_16x16x32_bf16 v[34:37], v[156:159], v[192:195], v[34:37]
	v_mfma_f32_16x16x32_bf16 v[26:29], v[164:167], v[192:195], v[26:29]
	v_mfma_f32_16x16x32_bf16 v[18:21], v[156:159], v[200:203], v[18:21]
	v_mfma_f32_16x16x32_bf16 v[10:13], v[164:167], v[200:203], v[10:13]
	s_barrier
	s_add_u32 s18, s18, 0xb0080
	s_addc_u32 s19, s19, 0
	s_add_i32 s20, s20, s27
	s_mov_b32 m0, s20
	s_nop 0
	global_load_lds_dwordx4 v134, s[18:19]
	s_add_i32 m0, s20, 0x2000
	s_nop 0
	global_load_lds_dwordx4 v136, s[18:19]
	s_waitcnt vmcnt(6)
	s_barrier
	v_mfma_f32_16x16x32_bf16 v[54:57], v[206:209], v[168:171], v[54:57]
	v_mfma_f32_16x16x32_bf16 v[46:49], v[216:219], v[168:171], v[46:49]
	v_mfma_f32_16x16x32_bf16 v[38:41], v[206:209], v[180:183], v[38:41]
	v_mfma_f32_16x16x32_bf16 v[30:33], v[216:219], v[180:183], v[30:33]
	v_mfma_f32_16x16x32_bf16 v[22:25], v[206:209], v[188:191], v[22:25]
	v_mfma_f32_16x16x32_bf16 v[14:17], v[216:219], v[188:191], v[14:17]
	v_mfma_f32_16x16x32_bf16 v[6:9], v[206:209], v[196:199], v[6:9]
	v_mfma_f32_16x16x32_bf16 v[2:5], v[216:219], v[196:199], v[2:5]
	v_mfma_f32_16x16x32_bf16 v[54:57], v[212:215], v[172:175], v[54:57]
	v_mfma_f32_16x16x32_bf16 v[46:49], v[220:223], v[172:175], v[46:49]
	v_mfma_f32_16x16x32_bf16 v[38:41], v[212:215], v[184:187], v[38:41]
	v_mfma_f32_16x16x32_bf16 v[30:33], v[220:223], v[184:187], v[30:33]
	v_mfma_f32_16x16x32_bf16 v[22:25], v[212:215], v[192:195], v[22:25]
	v_mfma_f32_16x16x32_bf16 v[14:17], v[220:223], v[192:195], v[14:17]
	v_mfma_f32_16x16x32_bf16 v[6:9], v[212:215], v[200:203], v[6:9]
	v_mfma_f32_16x16x32_bf16 v[2:5], v[220:223], v[200:203], v[2:5]
	s_add_i32 s54, s54, 2
	s_add_u32 s16, s16, 0x100
	s_addc_u32 s17, s17, 0
	s_add_u32 s52, s52, 0x100
	s_addc_u32 s53, s53, 0
	s_cmp_gt_u32 s54, 41
	s_barrier
	s_cbranch_scc1 .Lpeel_p10_exit
.LBB0_1197:
	ds_read_b128 v[152:155], v149
	ds_read_b128 v[156:159], v149 offset:1024
	ds_read_b128 v[160:163], v149 offset:2048
	ds_read_b128 v[164:167], v149 offset:3072
	s_add_u32 s18, s16, 0xfff50080
	s_addc_u32 s19, s17, -1
	s_cmp_eq_u32 s54, 40
	s_cselect_b32 s21, s3, s19
	s_cselect_b32 s20, s2, s18
	s_cselect_b32 s19, s5, s53
	s_cselect_b32 s18, s4, s52
	s_add_i32 m0, s30, 0xc000
	ds_read_b128 v[168:171], v150
	ds_read_b128 v[172:175], v150 offset:1024
	ds_read_b128 v[180:183], v150 offset:2048
	ds_read_b128 v[184:187], v150 offset:3072
	ds_read_b128 v[188:191], v150 offset:4096
	ds_read_b128 v[192:195], v150 offset:5120
	ds_read_b128 v[196:199], v150 offset:6144
	ds_read_b128 v[200:203], v150 offset:7168
	global_load_lds_dwordx4 v138, s[16:17]
	s_add_i32 m0, s30, 0xe000
	s_nop 0
	global_load_lds_dwordx4 v140, s[16:17]
	s_waitcnt lgkmcnt(8)
	s_barrier
	s_waitcnt lgkmcnt(0)
	v_mfma_f32_16x16x32_bf16 v[126:129], v[152:155], v[168:171], v[126:129]
	v_mfma_f32_16x16x32_bf16 v[122:125], v[160:163], v[168:171], v[122:125]
	v_mfma_f32_16x16x32_bf16 v[114:117], v[152:155], v[180:183], v[114:117]
	v_mfma_f32_16x16x32_bf16 v[106:109], v[160:163], v[180:183], v[106:109]
	v_mfma_f32_16x16x32_bf16 v[98:101], v[152:155], v[188:191], v[98:101]
	v_mfma_f32_16x16x32_bf16 v[90:93], v[160:163], v[188:191], v[90:93]
	v_mfma_f32_16x16x32_bf16 v[82:85], v[152:155], v[196:199], v[82:85]
	v_mfma_f32_16x16x32_bf16 v[74:77], v[160:163], v[196:199], v[74:77]
	v_mfma_f32_16x16x32_bf16 v[126:129], v[156:159], v[172:175], v[126:129]
	v_mfma_f32_16x16x32_bf16 v[122:125], v[164:167], v[172:175], v[122:125]
	v_mfma_f32_16x16x32_bf16 v[114:117], v[156:159], v[184:187], v[114:117]
	v_mfma_f32_16x16x32_bf16 v[106:109], v[164:167], v[184:187], v[106:109]
	v_mfma_f32_16x16x32_bf16 v[98:101], v[156:159], v[192:195], v[98:101]
	v_mfma_f32_16x16x32_bf16 v[90:93], v[164:167], v[192:195], v[90:93]
	v_mfma_f32_16x16x32_bf16 v[82:85], v[156:159], v[200:203], v[82:85]
	v_mfma_f32_16x16x32_bf16 v[74:77], v[164:167], v[200:203], v[74:77]
	s_barrier
	s_add_i32 s55, s41, s27
	s_add_u32 s98, s18, 0x80
	s_addc_u32 s99, s19, 0
	s_mov_b32 m0, s55
	ds_read_b128 v[206:209], v151
	ds_read_b128 v[212:215], v151 offset:1024
	ds_read_b128 v[216:219], v151 offset:2048
	ds_read_b128 v[220:223], v151 offset:3072
	global_load_lds_dwordx4 v134, s[18:19]
	s_add_i32 m0, s55, 0x2000
	s_nop 0
	global_load_lds_dwordx4 v136, s[18:19]
	s_barrier
	s_waitcnt lgkmcnt(0)
	v_mfma_f32_16x16x32_bf16 v[118:121], v[206:209], v[168:171], v[118:121]
	v_mfma_f32_16x16x32_bf16 v[110:113], v[216:219], v[168:171], v[110:113]
	v_mfma_f32_16x16x32_bf16 v[102:105], v[206:209], v[180:183], v[102:105]
	v_mfma_f32_16x16x32_bf16 v[94:97], v[216:219], v[180:183], v[94:97]
	v_mfma_f32_16x16x32_bf16 v[86:89], v[206:209], v[188:191], v[86:89]
	v_mfma_f32_16x16x32_bf16 v[78:81], v[216:219], v[188:191], v[78:81]
	v_mfma_f32_16x16x32_bf16 v[70:73], v[206:209], v[196:199], v[70:73]
	v_mfma_f32_16x16x32_bf16 v[66:69], v[216:219], v[196:199], v[66:69]
	v_mfma_f32_16x16x32_bf16 v[118:121], v[212:215], v[172:175], v[118:121]
	v_mfma_f32_16x16x32_bf16 v[110:113], v[220:223], v[172:175], v[110:113]
	v_mfma_f32_16x16x32_bf16 v[102:105], v[212:215], v[184:187], v[102:105]
	v_mfma_f32_16x16x32_bf16 v[94:97], v[220:223], v[184:187], v[94:97]
	v_mfma_f32_16x16x32_bf16 v[86:89], v[212:215], v[192:195], v[86:89]
	v_mfma_f32_16x16x32_bf16 v[78:81], v[220:223], v[192:195], v[78:81]
	v_mfma_f32_16x16x32_bf16 v[70:73], v[212:215], v[200:203], v[70:73]
	v_mfma_f32_16x16x32_bf16 v[66:69], v[220:223], v[200:203], v[66:69]
	s_mov_b32 m0, s30
	s_add_u32 s100, s20, 0x80
	s_addc_u32 s101, s21, 0
	s_barrier
	ds_read_b128 v[168:171], v150 offset:16384
	ds_read_b128 v[172:175], v150 offset:17408
	ds_read_b128 v[180:183], v150 offset:18432
	ds_read_b128 v[184:187], v150 offset:19456
	ds_read_b128 v[188:191], v150 offset:20480
	ds_read_b128 v[192:195], v150 offset:21504
	ds_read_b128 v[196:199], v150 offset:22528
	ds_read_b128 v[200:203], v150 offset:23552
	global_load_lds_dwordx4 v130, s[20:21]
	s_mov_b32 m0, s31
	s_nop 0
	global_load_lds_dwordx4 v132, s[20:21]
	s_barrier
	s_waitcnt lgkmcnt(0)
	v_mfma_f32_16x16x32_bf16 v[62:65], v[152:155], v[168:171], v[62:65]
	v_mfma_f32_16x16x32_bf16 v[58:61], v[160:163], v[168:171], v[58:61]
	v_mfma_f32_16x16x32_bf16 v[50:53], v[152:155], v[180:183], v[50:53]
	v_mfma_f32_16x16x32_bf16 v[42:45], v[160:163], v[180:183], v[42:45]
	v_mfma_f32_16x16x32_bf16 v[34:37], v[152:155], v[188:191], v[34:37]
	v_mfma_f32_16x16x32_bf16 v[26:29], v[160:163], v[188:191], v[26:29]
	v_mfma_f32_16x16x32_bf16 v[18:21], v[152:155], v[196:199], v[18:21]
	v_mfma_f32_16x16x32_bf16 v[10:13], v[160:163], v[196:199], v[10:13]
	v_mfma_f32_16x16x32_bf16 v[62:65], v[156:159], v[172:175], v[62:65]
	v_mfma_f32_16x16x32_bf16 v[58:61], v[164:167], v[172:175], v[58:61]
	v_mfma_f32_16x16x32_bf16 v[50:53], v[156:159], v[184:187], v[50:53]
	v_mfma_f32_16x16x32_bf16 v[42:45], v[164:167], v[184:187], v[42:45]
	v_mfma_f32_16x16x32_bf16 v[34:37], v[156:159], v[192:195], v[34:37]
	v_mfma_f32_16x16x32_bf16 v[26:29], v[164:167], v[192:195], v[26:29]
	v_mfma_f32_16x16x32_bf16 v[18:21], v[156:159], v[200:203], v[18:21]
	v_mfma_f32_16x16x32_bf16 v[10:13], v[164:167], v[200:203], v[10:13]
	s_barrier
	s_add_u32 s56, s18, 0xb0000
	s_addc_u32 s57, s19, 0
	s_add_i32 s55, s42, s27
	s_mov_b32 m0, s55
	s_nop 0
	global_load_lds_dwordx4 v134, s[56:57]
	s_add_i32 m0, s55, 0x2000
	s_nop 0
	global_load_lds_dwordx4 v136, s[56:57]
	s_waitcnt vmcnt(6)
	s_barrier
	v_mfma_f32_16x16x32_bf16 v[54:57], v[206:209], v[168:171], v[54:57]
	v_mfma_f32_16x16x32_bf16 v[46:49], v[216:219], v[168:171], v[46:49]
	v_mfma_f32_16x16x32_bf16 v[38:41], v[206:209], v[180:183], v[38:41]
	v_mfma_f32_16x16x32_bf16 v[30:33], v[216:219], v[180:183], v[30:33]
	v_mfma_f32_16x16x32_bf16 v[22:25], v[206:209], v[188:191], v[22:25]
	v_mfma_f32_16x16x32_bf16 v[14:17], v[216:219], v[188:191], v[14:17]
	v_mfma_f32_16x16x32_bf16 v[6:9], v[206:209], v[196:199], v[6:9]
	v_mfma_f32_16x16x32_bf16 v[2:5], v[216:219], v[196:199], v[2:5]
	v_mfma_f32_16x16x32_bf16 v[54:57], v[212:215], v[172:175], v[54:57]
	v_mfma_f32_16x16x32_bf16 v[46:49], v[220:223], v[172:175], v[46:49]
	v_mfma_f32_16x16x32_bf16 v[38:41], v[212:215], v[184:187], v[38:41]
	v_mfma_f32_16x16x32_bf16 v[30:33], v[220:223], v[184:187], v[30:33]
	v_mfma_f32_16x16x32_bf16 v[22:25], v[212:215], v[192:195], v[22:25]
	v_mfma_f32_16x16x32_bf16 v[14:17], v[220:223], v[192:195], v[14:17]
	v_mfma_f32_16x16x32_bf16 v[6:9], v[212:215], v[200:203], v[6:9]
	v_mfma_f32_16x16x32_bf16 v[2:5], v[220:223], v[200:203], v[2:5]
	s_add_i32 s55, 0, 0x18000
	v_add_u32_e32 v164, s55, v148
	s_barrier
	ds_read_b128 v[152:155], v164
	ds_read_b128 v[156:159], v164 offset:1024
	ds_read_b128 v[160:163], v164 offset:2048
	ds_read_b128 v[164:167], v164 offset:3072
	s_add_u32 s20, s20, 0xb0000
	s_addc_u32 s21, s21, 0
	s_mov_b32 m0, s33
	ds_read_b128 v[168:171], v150 offset:32768
	ds_read_b128 v[172:175], v150 offset:33792
	ds_read_b128 v[180:183], v150 offset:34816
	ds_read_b128 v[184:187], v150 offset:35840
	ds_read_b128 v[188:191], v150 offset:36864
	ds_read_b128 v[192:195], v150 offset:37888
	ds_read_b128 v[196:199], v150 offset:38912
	ds_read_b128 v[200:203], v150 offset:39936
	global_load_lds_dwordx4 v130, s[20:21]
	s_mov_b32 m0, s34
	s_nop 0
	global_load_lds_dwordx4 v132, s[20:21]
	s_waitcnt lgkmcnt(8)
	s_barrier
	s_waitcnt lgkmcnt(0)
	v_mfma_f32_16x16x32_bf16 v[126:129], v[152:155], v[168:171], v[126:129]
	v_mfma_f32_16x16x32_bf16 v[122:125], v[160:163], v[168:171], v[122:125]
	v_mfma_f32_16x16x32_bf16 v[114:117], v[152:155], v[180:183], v[114:117]
	v_mfma_f32_16x16x32_bf16 v[106:109], v[160:163], v[180:183], v[106:109]
	v_mfma_f32_16x16x32_bf16 v[98:101], v[152:155], v[188:191], v[98:101]
	v_mfma_f32_16x16x32_bf16 v[90:93], v[160:163], v[188:191], v[90:93]
	v_mfma_f32_16x16x32_bf16 v[82:85], v[152:155], v[196:199], v[82:85]
	v_mfma_f32_16x16x32_bf16 v[74:77], v[160:163], v[196:199], v[74:77]
	v_mfma_f32_16x16x32_bf16 v[126:129], v[156:159], v[172:175], v[126:129]
	v_mfma_f32_16x16x32_bf16 v[122:125], v[164:167], v[172:175], v[122:125]
	v_mfma_f32_16x16x32_bf16 v[114:117], v[156:159], v[184:187], v[114:117]
	v_mfma_f32_16x16x32_bf16 v[106:109], v[164:167], v[184:187], v[106:109]
	v_mfma_f32_16x16x32_bf16 v[98:101], v[156:159], v[192:195], v[98:101]
	v_mfma_f32_16x16x32_bf16 v[90:93], v[164:167], v[192:195], v[90:93]
	v_mfma_f32_16x16x32_bf16 v[82:85], v[156:159], v[200:203], v[82:85]
	v_mfma_f32_16x16x32_bf16 v[74:77], v[164:167], v[200:203], v[74:77]
	s_barrier
	s_add_i32 s20, 0, 0x1c000
	s_add_i32 s21, s55, s27
	v_add_u32_e32 v179, s20, v148
	s_mov_b32 m0, s21
	ds_read_b128 v[206:209], v179
	ds_read_b128 v[212:215], v179 offset:1024
	ds_read_b128 v[216:219], v179 offset:2048
	ds_read_b128 v[220:223], v179 offset:3072
	global_load_lds_dwordx4 v134, s[98:99]
	s_add_i32 m0, s21, 0x2000
	s_nop 0
	global_load_lds_dwordx4 v136, s[98:99]
	s_barrier
	s_waitcnt lgkmcnt(0)
	v_mfma_f32_16x16x32_bf16 v[118:121], v[206:209], v[168:171], v[118:121]
	v_mfma_f32_16x16x32_bf16 v[110:113], v[216:219], v[168:171], v[110:113]
	v_mfma_f32_16x16x32_bf16 v[102:105], v[206:209], v[180:183], v[102:105]
	v_mfma_f32_16x16x32_bf16 v[94:97], v[216:219], v[180:183], v[94:97]
	v_mfma_f32_16x16x32_bf16 v[86:89], v[206:209], v[188:191], v[86:89]
	v_mfma_f32_16x16x32_bf16 v[78:81], v[216:219], v[188:191], v[78:81]
	v_mfma_f32_16x16x32_bf16 v[70:73], v[206:209], v[196:199], v[70:73]
	v_mfma_f32_16x16x32_bf16 v[66:69], v[216:219], v[196:199], v[66:69]
	v_mfma_f32_16x16x32_bf16 v[118:121], v[212:215], v[172:175], v[118:121]
	v_mfma_f32_16x16x32_bf16 v[110:113], v[220:223], v[172:175], v[110:113]
	v_mfma_f32_16x16x32_bf16 v[102:105], v[212:215], v[184:187], v[102:105]
	v_mfma_f32_16x16x32_bf16 v[94:97], v[220:223], v[184:187], v[94:97]
	v_mfma_f32_16x16x32_bf16 v[86:89], v[212:215], v[192:195], v[86:89]
	v_mfma_f32_16x16x32_bf16 v[78:81], v[220:223], v[192:195], v[78:81]
	v_mfma_f32_16x16x32_bf16 v[70:73], v[212:215], v[200:203], v[70:73]
	v_mfma_f32_16x16x32_bf16 v[66:69], v[220:223], v[200:203], v[66:69]
	s_mov_b32 m0, s37
	s_barrier
	ds_read_b128 v[168:171], v150 offset:49152
	ds_read_b128 v[172:175], v150 offset:50176
	ds_read_b128 v[180:183], v150 offset:51200
	ds_read_b128 v[184:187], v150 offset:52224
	ds_read_b128 v[188:191], v150 offset:53248
	ds_read_b128 v[192:195], v150 offset:54272
	ds_read_b128 v[196:199], v150 offset:55296
	ds_read_b128 v[200:203], v150 offset:56320
	global_load_lds_dwordx4 v130, s[100:101]
	s_mov_b32 m0, s38
	s_nop 0
	global_load_lds_dwordx4 v132, s[100:101]
	s_barrier
	s_waitcnt lgkmcnt(0)
	v_mfma_f32_16x16x32_bf16 v[62:65], v[152:155], v[168:171], v[62:65]
	v_mfma_f32_16x16x32_bf16 v[58:61], v[160:163], v[168:171], v[58:61]
	v_mfma_f32_16x16x32_bf16 v[50:53], v[152:155], v[180:183], v[50:53]
	v_mfma_f32_16x16x32_bf16 v[42:45], v[160:163], v[180:183], v[42:45]
	v_mfma_f32_16x16x32_bf16 v[34:37], v[152:155], v[188:191], v[34:37]
	v_mfma_f32_16x16x32_bf16 v[26:29], v[160:163], v[188:191], v[26:29]
	v_mfma_f32_16x16x32_bf16 v[18:21], v[152:155], v[196:199], v[18:21]
	v_mfma_f32_16x16x32_bf16 v[10:13], v[160:163], v[196:199], v[10:13]
	v_mfma_f32_16x16x32_bf16 v[62:65], v[156:159], v[172:175], v[62:65]
	v_mfma_f32_16x16x32_bf16 v[58:61], v[164:167], v[172:175], v[58:61]
	v_mfma_f32_16x16x32_bf16 v[50:53], v[156:159], v[184:187], v[50:53]
	v_mfma_f32_16x16x32_bf16 v[42:45], v[164:167], v[184:187], v[42:45]
	v_mfma_f32_16x16x32_bf16 v[34:37], v[156:159], v[192:195], v[34:37]
	v_mfma_f32_16x16x32_bf16 v[26:29], v[164:167], v[192:195], v[26:29]
	v_mfma_f32_16x16x32_bf16 v[18:21], v[156:159], v[200:203], v[18:21]
	v_mfma_f32_16x16x32_bf16 v[10:13], v[164:167], v[200:203], v[10:13]
	s_barrier
	s_add_u32 s18, s18, 0xb0080
	s_addc_u32 s19, s19, 0
	s_add_i32 s20, s20, s27
	s_mov_b32 m0, s20
	s_nop 0
	global_load_lds_dwordx4 v134, s[18:19]
	s_add_i32 m0, s20, 0x2000
	s_nop 0
	global_load_lds_dwordx4 v136, s[18:19]
	s_waitcnt vmcnt(6)
	s_barrier
	v_mfma_f32_16x16x32_bf16 v[54:57], v[206:209], v[168:171], v[54:57]
	v_mfma_f32_16x16x32_bf16 v[46:49], v[216:219], v[168:171], v[46:49]
	v_mfma_f32_16x16x32_bf16 v[38:41], v[206:209], v[180:183], v[38:41]
	v_mfma_f32_16x16x32_bf16 v[30:33], v[216:219], v[180:183], v[30:33]
	v_mfma_f32_16x16x32_bf16 v[22:25], v[206:209], v[188:191], v[22:25]
	v_mfma_f32_16x16x32_bf16 v[14:17], v[216:219], v[188:191], v[14:17]
	v_mfma_f32_16x16x32_bf16 v[6:9], v[206:209], v[196:199], v[6:9]
	v_mfma_f32_16x16x32_bf16 v[2:5], v[216:219], v[196:199], v[2:5]
	v_mfma_f32_16x16x32_bf16 v[54:57], v[212:215], v[172:175], v[54:57]
	v_mfma_f32_16x16x32_bf16 v[46:49], v[220:223], v[172:175], v[46:49]
	v_mfma_f32_16x16x32_bf16 v[38:41], v[212:215], v[184:187], v[38:41]
	v_mfma_f32_16x16x32_bf16 v[30:33], v[220:223], v[184:187], v[30:33]
	v_mfma_f32_16x16x32_bf16 v[22:25], v[212:215], v[192:195], v[22:25]
	v_mfma_f32_16x16x32_bf16 v[14:17], v[220:223], v[192:195], v[14:17]
	v_mfma_f32_16x16x32_bf16 v[6:9], v[212:215], v[200:203], v[6:9]
	v_mfma_f32_16x16x32_bf16 v[2:5], v[220:223], v[200:203], v[2:5]
	s_add_i32 s54, s54, 2
	s_add_u32 s16, s16, 0x100
	s_addc_u32 s17, s17, 0
	s_add_u32 s52, s52, 0x100
	s_addc_u32 s53, s53, 0
	s_cmp_gt_u32 s54, 41
	s_barrier
	s_cbranch_scc0 .LBB0_1197
